# the 64 per-block s_setprio flips removed from the four GEMM K-loops (timing-only change)
# speedup vs baseline: 1.0068x; 1.0028x over previous
; #define PG8_STAGE(bufoff, gbase, voff) do { _Pragma("unroll") for (int _i = 0; _i < 2; ++_i) \
;         __builtin_amdgcn_global_load_lds((const unsigned*)((const char*)(gbase) + (voff)[_i]), (PG8_LAS unsigned*)(lds + (bufoff) + ldsw + _i * 8192), 16, 0, 0); } while (0)
; #define PG8_LDA(dst, b, h) do { _Pragma("unroll") for (int m = 0; m < 4; ++m) _Pragma("unroll") for (int k = 0; k < 2; ++k) dst[m][k] = *(const PG8_LAS bf16x8*)(lds + PG8_SA(b, h) + aoff + m * 2048 + k * 1024); } while (0)
; #define PG8_LDB(dst, b, h) do { _Pragma("unroll") for (int n = 0; n < 2; ++n) _Pragma("unroll") for (int k = 0; k < 2; ++k) dst[n][k] = *(const PG8_LAS bf16x8*)(lds + PG8_SB(b, h) + boff + n * 2048 + k * 1024); } while (0)
; #define PG8_MMA(ai, bj, At, Bt) do { __builtin_amdgcn_s_setprio(1); _Pragma("unroll") for (int m = 0; m < 4; ++m) _Pragma("unroll") for (int n = 0; n < 2; ++n) _Pragma("unroll") for (int k = 0; k < 2; ++k) \
;         acc[ai][bj][m][n] = __builtin_amdgcn_mfma_f32_16x16x32_bf16(Bt[n][k], At[m][k], acc[ai][bj][m][n], 0, 0, 0); __builtin_amdgcn_s_setprio(0); } while (0)
; #define PG8_WAIT_V(n) asm volatile("s_waitcnt vmcnt(" #n ")" ::: "memory")
; #define PG8_BAR __builtin_amdgcn_s_barrier()
; template <class Epi, class Sched, bool ALIGN_EPI = false, bool SP2 = false>
; __device__ __forceinline__ void gemm_phase(PG8_LAS unsigned char* lds, const Gemm g, const Sched& S, const Epi& E) {
;     ...
;         for (int t = 0; t < nt; t += 2) {
;             const bool last = (t == nt - 2);
;             const char* a1 = cA + (size_t)(t + 1) * kstep;
;             const char* a2 = last ? nA : cA + (size_t)(t + 2) * kstep; const char* b2 = last ? nB : cB + (size_t)(t + 2) * kstep;
;             const char* a3 = a2 + kstep; const char* b3 = b2 + kstep;
;             if (last && has_next) S.a_ready(nxt);
;             if constexpr (SP2) {
;             PG8_LDB(B0, 0, 0); PG8_LDB(B1, 0, 1); PG8_SCHED; PG8_LDA(At, 0, 0); PG8_STAGE(PG8_SA(1, 1), a1 + hstep, voffA);
;             PG8_WAIT_V(8); PG8_WAIT_L(0); PG8_BAR; PG8_MMA(0, 0, At, B0); PG8_MMA(0, 1, At, B1); PG8_BAR; PG8_SCHED;
;             PG8_LDA(At, 0, 1); PG8_STAGE(PG8_SB(0, 0), b2, voffB); PG8_STAGE(PG8_SB(0, 1), b2 + hstep, voffB); PG8_STAGE(PG8_SA(0, 0), a2, voffA);
;             PG8_WAIT_V(8); PG8_WAIT_L(0); PG8_BAR; PG8_MMA(1, 0, At, B0); PG8_MMA(1, 1, At, B1); PG8_BAR; PG8_SCHED;
.LBB0_138:
	s_add_u32 s22, s56, 0xfff80080
	s_addc_u32 s23, s57, -1
	s_add_i32 s89, 0, 0x10000
	s_cmp_eq_u32 s88, 28
	s_cselect_b32 s49, s47, s23
	s_cselect_b32 s48, s84, s22
	s_cselect_b32 s35, s45, s87
	s_cselect_b32 s34, s85, s86
	s_add_i32 s90, 0, 0x14000
	v_add_u32_e32 v156, s89, v149
	v_add_u32_e32 v172, s90, v149
	ds_read_b128 v[140:143], v156
	ds_read_b128 v[144:147], v156 offset:1024
	ds_read_b128 v[152:155], v156 offset:2048
	ds_read_b128 v[156:159], v156 offset:3072
	ds_read_b128 v[160:163], v172
	ds_read_b128 v[164:167], v172 offset:1024
	ds_read_b128 v[168:171], v172 offset:2048
	ds_read_b128 v[172:175], v172 offset:3072
	v_lshl_add_u64 v[208:209], s[56:57], 0, v[136:137]
	s_add_i32 m0, s75, 0xc000
	ds_read_b128 v[176:179], v151
	ds_read_b128 v[180:183], v151 offset:1024
	ds_read_b128 v[184:187], v151 offset:2048
	ds_read_b128 v[188:191], v151 offset:3072
	ds_read_b128 v[192:195], v151 offset:4096
	ds_read_b128 v[196:199], v151 offset:5120
	ds_read_b128 v[200:203], v151 offset:6144
	ds_read_b128 v[204:207], v151 offset:7168
	global_load_lds_dwordx4 v[208:209], off
	v_lshl_add_u64 v[208:209], s[56:57], 0, v[138:139]
	s_add_i32 m0, s75, 0xe000
	s_nop 0
	global_load_lds_dwordx4 v[208:209], off
	s_waitcnt vmcnt(8)
	s_waitcnt lgkmcnt(0)
	s_barrier
	s_waitcnt lgkmcnt(0)
	v_mfma_f32_16x16x32_bf16 v[126:129], v[140:143], v[176:179], v[126:129]
	v_mfma_f32_16x16x32_bf16 v[122:125], v[152:155], v[176:179], v[122:125]
	v_mfma_f32_16x16x32_bf16 v[110:113], v[140:143], v[184:187], v[110:113]
	v_mfma_f32_16x16x32_bf16 v[106:109], v[152:155], v[184:187], v[106:109]
	v_mfma_f32_16x16x32_bf16 v[94:97], v[140:143], v[192:195], v[94:97]
	v_mfma_f32_16x16x32_bf16 v[90:93], v[152:155], v[192:195], v[90:93]
	v_mfma_f32_16x16x32_bf16 v[86:89], v[140:143], v[200:203], v[86:89]
	v_mfma_f32_16x16x32_bf16 v[78:81], v[152:155], v[200:203], v[78:81]
	v_mfma_f32_16x16x32_bf16 v[126:129], v[144:147], v[180:183], v[126:129]
	v_mfma_f32_16x16x32_bf16 v[122:125], v[156:159], v[180:183], v[122:125]
	v_mfma_f32_16x16x32_bf16 v[110:113], v[144:147], v[188:191], v[110:113]
	v_mfma_f32_16x16x32_bf16 v[106:109], v[156:159], v[188:191], v[106:109]
	v_mfma_f32_16x16x32_bf16 v[94:97], v[144:147], v[196:199], v[94:97]
	v_mfma_f32_16x16x32_bf16 v[90:93], v[156:159], v[196:199], v[90:93]
	v_mfma_f32_16x16x32_bf16 v[86:89], v[144:147], v[204:207], v[86:89]
	v_mfma_f32_16x16x32_bf16 v[78:81], v[156:159], v[204:207], v[78:81]
	v_mfma_f32_16x16x32_bf16 v[118:121], v[160:163], v[176:179], v[118:121]
	v_mfma_f32_16x16x32_bf16 v[114:117], v[168:171], v[176:179], v[114:117]
	v_mfma_f32_16x16x32_bf16 v[102:105], v[160:163], v[184:187], v[102:105]
	v_mfma_f32_16x16x32_bf16 v[98:101], v[168:171], v[184:187], v[98:101]
	v_mfma_f32_16x16x32_bf16 v[82:85], v[160:163], v[192:195], v[82:85]
	v_mfma_f32_16x16x32_bf16 v[74:77], v[168:171], v[192:195], v[74:77]
	v_mfma_f32_16x16x32_bf16 v[70:73], v[160:163], v[200:203], v[70:73]
	v_mfma_f32_16x16x32_bf16 v[66:69], v[168:171], v[200:203], v[66:69]
	v_mfma_f32_16x16x32_bf16 v[118:121], v[164:167], v[180:183], v[118:121]
	v_mfma_f32_16x16x32_bf16 v[114:117], v[172:175], v[180:183], v[114:117]
	v_mfma_f32_16x16x32_bf16 v[102:105], v[164:167], v[188:191], v[102:105]
	v_mfma_f32_16x16x32_bf16 v[98:101], v[172:175], v[188:191], v[98:101]
	v_mfma_f32_16x16x32_bf16 v[82:85], v[164:167], v[196:199], v[82:85]
	v_mfma_f32_16x16x32_bf16 v[74:77], v[172:175], v[196:199], v[74:77]
	v_mfma_f32_16x16x32_bf16 v[70:73], v[164:167], v[204:207], v[70:73]
	v_mfma_f32_16x16x32_bf16 v[66:69], v[172:175], v[204:207], v[66:69]
	s_barrier
	s_add_i32 s22, s89, s74
	v_lshl_add_u64 v[208:209], s[34:35], 0, v[0:1]
	s_mov_b32 m0, s22
	ds_read_b128 v[176:179], v151 offset:16384
	ds_read_b128 v[180:183], v151 offset:17408
	ds_read_b128 v[184:187], v151 offset:18432
	ds_read_b128 v[188:191], v151 offset:19456
	ds_read_b128 v[192:195], v151 offset:20480
	ds_read_b128 v[196:199], v151 offset:21504
	ds_read_b128 v[200:203], v151 offset:22528
	ds_read_b128 v[204:207], v151 offset:23552
	global_load_lds_dwordx4 v[208:209], off
	s_add_i32 m0, s22, 0x2000
	s_add_u32 s22, s34, 0x80000
	v_lshl_add_u64 v[210:211], s[34:35], 0, v[130:131]
	s_addc_u32 s23, s35, 0
	s_add_i32 s89, s90, s74
	global_load_lds_dwordx4 v[210:211], off
	v_lshl_add_u64 v[216:217], s[22:23], 0, v[0:1]
	s_mov_b32 m0, s89
	v_lshl_add_u64 v[220:221], s[48:49], 0, v[132:133]
	global_load_lds_dwordx4 v[216:217], off
	v_lshl_add_u64 v[216:217], s[22:23], 0, v[130:131]
	s_add_i32 m0, s89, 0x2000
	s_nop 0
	global_load_lds_dwordx4 v[216:217], off
	v_lshl_add_u64 v[216:217], s[48:49], 0, v[134:135]
	s_mov_b32 m0, s75
	s_nop 0
	global_load_lds_dwordx4 v[216:217], off
	s_mov_b32 m0, s76
	s_nop 0
	global_load_lds_dwordx4 v[220:221], off
	s_waitcnt vmcnt(8)
	s_waitcnt lgkmcnt(0)
	s_barrier
; #define PG8_STAGE(bufoff, gbase, voff) do { _Pragma("unroll") for (int _i = 0; _i < 2; ++_i) \
;         __builtin_amdgcn_global_load_lds((const unsigned*)((const char*)(gbase) + (voff)[_i]), (PG8_LAS unsigned*)(lds + (bufoff) + ldsw + _i * 8192), 16, 0, 0); } while (0)
; #define PG8_LDA(dst, b, h) do { _Pragma("unroll") for (int m = 0; m < 4; ++m) _Pragma("unroll") for (int k = 0; k < 2; ++k) dst[m][k] = *(const PG8_LAS bf16x8*)(lds + PG8_SA(b, h) + aoff + m * 2048 + k * 1024); } while (0)
; #define PG8_LDB(dst, b, h) do { _Pragma("unroll") for (int n = 0; n < 2; ++n) _Pragma("unroll") for (int k = 0; k < 2; ++k) dst[n][k] = *(const PG8_LAS bf16x8*)(lds + PG8_SB(b, h) + boff + n * 2048 + k * 1024); } while (0)
; #define PG8_MMA(ai, bj, At, Bt) do { __builtin_amdgcn_s_setprio(1); _Pragma("unroll") for (int m = 0; m < 4; ++m) _Pragma("unroll") for (int n = 0; n < 2; ++n) _Pragma("unroll") for (int k = 0; k < 2; ++k) \
;         acc[ai][bj][m][n] = __builtin_amdgcn_mfma_f32_16x16x32_bf16(Bt[n][k], At[m][k], acc[ai][bj][m][n], 0, 0, 0); __builtin_amdgcn_s_setprio(0); } while (0)
; #define PG8_WAIT_V(n) asm volatile("s_waitcnt vmcnt(" #n ")" ::: "memory")
; #define PG8_WAIT_L(n) asm volatile("s_waitcnt lgkmcnt(" #n ")" ::: "memory")
; #define PG8_BAR __builtin_amdgcn_s_barrier()
; #define PG8_SCHED __builtin_amdgcn_sched_barrier(0)
; template <class Epi, class Sched, bool ALIGN_EPI = false, bool SP2 = false>
; __device__ __forceinline__ void gemm_phase(PG8_LAS unsigned char* lds, const Gemm g, const Sched& S, const Epi& E) {
;     ...
;             PG8_WAIT_V(8); PG8_WAIT_L(0); PG8_BAR; PG8_MMA(1, 0, At, B0); PG8_MMA(1, 1, At, B1); PG8_BAR; PG8_SCHED;
;             PG8_LDB(B0, 1, 0); PG8_LDB(B1, 1, 1); PG8_SCHED; PG8_LDA(At, 1, 0); PG8_STAGE(PG8_SA(0, 1), a2 + hstep, voffA);
;             PG8_WAIT_V(8); PG8_WAIT_L(0); PG8_BAR; PG8_MMA(0, 0, At, B0); PG8_MMA(0, 1, At, B1); PG8_BAR; PG8_SCHED;
;             PG8_LDA(At, 1, 1); PG8_STAGE(PG8_SB(1, 0), b3, voffB); PG8_STAGE(PG8_SB(1, 1), b3 + hstep, voffB); PG8_STAGE(PG8_SA(1, 0), a3, voffA);
	s_waitcnt lgkmcnt(0)
	v_mfma_f32_16x16x32_bf16 v[62:65], v[140:143], v[176:179], v[62:65]
	v_mfma_f32_16x16x32_bf16 v[58:61], v[152:155], v[176:179], v[58:61]
	v_mfma_f32_16x16x32_bf16 v[50:53], v[140:143], v[184:187], v[50:53]
	v_mfma_f32_16x16x32_bf16 v[42:45], v[152:155], v[184:187], v[42:45]
	v_mfma_f32_16x16x32_bf16 v[34:37], v[140:143], v[192:195], v[34:37]
	v_mfma_f32_16x16x32_bf16 v[26:29], v[152:155], v[192:195], v[26:29]
	v_mfma_f32_16x16x32_bf16 v[14:17], v[140:143], v[200:203], v[14:17]
	v_mfma_f32_16x16x32_bf16 v[10:13], v[152:155], v[200:203], v[10:13]
	v_mfma_f32_16x16x32_bf16 v[62:65], v[144:147], v[180:183], v[62:65]
	v_mfma_f32_16x16x32_bf16 v[58:61], v[156:159], v[180:183], v[58:61]
	v_mfma_f32_16x16x32_bf16 v[50:53], v[144:147], v[188:191], v[50:53]
	v_mfma_f32_16x16x32_bf16 v[42:45], v[156:159], v[188:191], v[42:45]
	v_mfma_f32_16x16x32_bf16 v[34:37], v[144:147], v[196:199], v[34:37]
	v_mfma_f32_16x16x32_bf16 v[26:29], v[156:159], v[196:199], v[26:29]
	v_mfma_f32_16x16x32_bf16 v[14:17], v[144:147], v[204:207], v[14:17]
	v_mfma_f32_16x16x32_bf16 v[10:13], v[156:159], v[204:207], v[10:13]
	v_mfma_f32_16x16x32_bf16 v[54:57], v[160:163], v[176:179], v[54:57]
	v_mfma_f32_16x16x32_bf16 v[46:49], v[168:171], v[176:179], v[46:49]
	v_mfma_f32_16x16x32_bf16 v[38:41], v[160:163], v[184:187], v[38:41]
	v_mfma_f32_16x16x32_bf16 v[30:33], v[168:171], v[184:187], v[30:33]
	v_mfma_f32_16x16x32_bf16 v[22:25], v[160:163], v[192:195], v[22:25]
	v_mfma_f32_16x16x32_bf16 v[18:21], v[168:171], v[192:195], v[18:21]
	v_mfma_f32_16x16x32_bf16 v[6:9], v[160:163], v[200:203], v[6:9]
	v_mfma_f32_16x16x32_bf16 v[2:5], v[168:171], v[200:203], v[2:5]
	v_mfma_f32_16x16x32_bf16 v[54:57], v[164:167], v[180:183], v[54:57]
	v_mfma_f32_16x16x32_bf16 v[46:49], v[172:175], v[180:183], v[46:49]
	v_mfma_f32_16x16x32_bf16 v[38:41], v[164:167], v[188:191], v[38:41]
	v_mfma_f32_16x16x32_bf16 v[30:33], v[172:175], v[188:191], v[30:33]
	v_mfma_f32_16x16x32_bf16 v[22:25], v[164:167], v[196:199], v[22:25]
	v_mfma_f32_16x16x32_bf16 v[18:21], v[172:175], v[196:199], v[18:21]
	v_mfma_f32_16x16x32_bf16 v[6:9], v[164:167], v[204:207], v[6:9]
	v_mfma_f32_16x16x32_bf16 v[2:5], v[172:175], v[204:207], v[2:5]
	s_barrier
	s_add_i32 s89, 0, 0x18000
	s_add_i32 s90, 0, 0x1c000
	v_add_u32_e32 v156, s89, v149
	v_add_u32_e32 v172, s90, v149
	ds_read_b128 v[140:143], v156
	ds_read_b128 v[144:147], v156 offset:1024
	ds_read_b128 v[152:155], v156 offset:2048
	ds_read_b128 v[156:159], v156 offset:3072
	ds_read_b128 v[160:163], v172
	ds_read_b128 v[164:167], v172 offset:1024
	ds_read_b128 v[168:171], v172 offset:2048
	ds_read_b128 v[172:175], v172 offset:3072
	s_add_u32 s22, s48, 0x80000
	s_addc_u32 s23, s49, 0
	s_mov_b32 m0, s77
	v_lshl_add_u64 v[222:223], s[22:23], 0, v[134:135]
	ds_read_b128 v[176:179], v151 offset:32768
	ds_read_b128 v[180:183], v151 offset:33792
	ds_read_b128 v[184:187], v151 offset:34816
	ds_read_b128 v[188:191], v151 offset:35840
	ds_read_b128 v[192:195], v151 offset:36864
	ds_read_b128 v[196:199], v151 offset:37888
	ds_read_b128 v[200:203], v151 offset:38912
	ds_read_b128 v[204:207], v151 offset:39936
	global_load_lds_dwordx4 v[222:223], off
	v_lshl_add_u64 v[222:223], s[22:23], 0, v[132:133]
	s_mov_b32 m0, s78
	s_nop 0
	global_load_lds_dwordx4 v[222:223], off
	s_waitcnt vmcnt(8)
	s_waitcnt lgkmcnt(0)
	s_barrier
	s_waitcnt lgkmcnt(0)
	v_mfma_f32_16x16x32_bf16 v[126:129], v[140:143], v[176:179], v[126:129]
	v_mfma_f32_16x16x32_bf16 v[122:125], v[152:155], v[176:179], v[122:125]
	v_mfma_f32_16x16x32_bf16 v[110:113], v[140:143], v[184:187], v[110:113]
	v_mfma_f32_16x16x32_bf16 v[106:109], v[152:155], v[184:187], v[106:109]
	v_mfma_f32_16x16x32_bf16 v[94:97], v[140:143], v[192:195], v[94:97]
	v_mfma_f32_16x16x32_bf16 v[90:93], v[152:155], v[192:195], v[90:93]
	v_mfma_f32_16x16x32_bf16 v[86:89], v[140:143], v[200:203], v[86:89]
	v_mfma_f32_16x16x32_bf16 v[78:81], v[152:155], v[200:203], v[78:81]
	v_mfma_f32_16x16x32_bf16 v[126:129], v[144:147], v[180:183], v[126:129]
	v_mfma_f32_16x16x32_bf16 v[122:125], v[156:159], v[180:183], v[122:125]
	v_mfma_f32_16x16x32_bf16 v[110:113], v[144:147], v[188:191], v[110:113]
	v_mfma_f32_16x16x32_bf16 v[106:109], v[156:159], v[188:191], v[106:109]
	v_mfma_f32_16x16x32_bf16 v[94:97], v[144:147], v[196:199], v[94:97]
	v_mfma_f32_16x16x32_bf16 v[90:93], v[156:159], v[196:199], v[90:93]
	v_mfma_f32_16x16x32_bf16 v[86:89], v[144:147], v[204:207], v[86:89]
	v_mfma_f32_16x16x32_bf16 v[78:81], v[156:159], v[204:207], v[78:81]
	v_mfma_f32_16x16x32_bf16 v[118:121], v[160:163], v[176:179], v[118:121]
	v_mfma_f32_16x16x32_bf16 v[114:117], v[168:171], v[176:179], v[114:117]
	v_mfma_f32_16x16x32_bf16 v[102:105], v[160:163], v[184:187], v[102:105]
	v_mfma_f32_16x16x32_bf16 v[98:101], v[168:171], v[184:187], v[98:101]
	v_mfma_f32_16x16x32_bf16 v[82:85], v[160:163], v[192:195], v[82:85]
	v_mfma_f32_16x16x32_bf16 v[74:77], v[168:171], v[192:195], v[74:77]
	v_mfma_f32_16x16x32_bf16 v[70:73], v[160:163], v[200:203], v[70:73]
	v_mfma_f32_16x16x32_bf16 v[66:69], v[168:171], v[200:203], v[66:69]
	v_mfma_f32_16x16x32_bf16 v[118:121], v[164:167], v[180:183], v[118:121]
	v_mfma_f32_16x16x32_bf16 v[114:117], v[172:175], v[180:183], v[114:117]
	v_mfma_f32_16x16x32_bf16 v[102:105], v[164:167], v[188:191], v[102:105]
	v_mfma_f32_16x16x32_bf16 v[98:101], v[172:175], v[188:191], v[98:101]
	v_mfma_f32_16x16x32_bf16 v[82:85], v[164:167], v[196:199], v[82:85]
	v_mfma_f32_16x16x32_bf16 v[74:77], v[172:175], v[196:199], v[74:77]
	v_mfma_f32_16x16x32_bf16 v[70:73], v[164:167], v[204:207], v[70:73]
	v_mfma_f32_16x16x32_bf16 v[66:69], v[172:175], v[204:207], v[66:69]
	s_barrier
; #define PG8_STAGE(bufoff, gbase, voff) do { _Pragma("unroll") for (int _i = 0; _i < 2; ++_i) \
;         __builtin_amdgcn_global_load_lds((const unsigned*)((const char*)(gbase) + (voff)[_i]), (PG8_LAS unsigned*)(lds + (bufoff) + ldsw + _i * 8192), 16, 0, 0); } while (0)
; #define PG8_LDA(dst, b, h) do { _Pragma("unroll") for (int m = 0; m < 4; ++m) _Pragma("unroll") for (int k = 0; k < 2; ++k) dst[m][k] = *(const PG8_LAS bf16x8*)(lds + PG8_SA(b, h) + aoff + m * 2048 + k * 1024); } while (0)
; #define PG8_MMA(ai, bj, At, Bt) do { __builtin_amdgcn_s_setprio(1); _Pragma("unroll") for (int m = 0; m < 4; ++m) _Pragma("unroll") for (int n = 0; n < 2; ++n) _Pragma("unroll") for (int k = 0; k < 2; ++k) \
;         acc[ai][bj][m][n] = __builtin_amdgcn_mfma_f32_16x16x32_bf16(Bt[n][k], At[m][k], acc[ai][bj][m][n], 0, 0, 0); __builtin_amdgcn_s_setprio(0); } while (0)
; #define PG8_WAIT_V(n) asm volatile("s_waitcnt vmcnt(" #n ")" ::: "memory")
; #define PG8_WAIT_L(n) asm volatile("s_waitcnt lgkmcnt(" #n ")" ::: "memory")
; #define PG8_BAR __builtin_amdgcn_s_barrier()
; #define PG8_SCHED __builtin_amdgcn_sched_barrier(0)
; template <class Epi, class Sched, bool ALIGN_EPI = false, bool SP2 = false>
; __device__ __forceinline__ void gemm_phase(PG8_LAS unsigned char* lds, const Gemm g, const Sched& S, const Epi& E) {
;     ...
;             PG8_LDA(At, 1, 1); PG8_STAGE(PG8_SB(1, 0), b3, voffB); PG8_STAGE(PG8_SB(1, 1), b3 + hstep, voffB); PG8_STAGE(PG8_SA(1, 0), a3, voffA);
;             PG8_WAIT_V(8); PG8_WAIT_L(0); PG8_BAR; PG8_MMA(1, 0, At, B0); PG8_MMA(1, 1, At, B1); PG8_BAR; PG8_SCHED;
	s_add_i32 s22, s89, s74
	v_lshl_add_u64 v[208:209], v[208:209], 0, s[30:31]
	s_mov_b32 m0, s22
	ds_read_b128 v[176:179], v151 offset:49152
	ds_read_b128 v[180:183], v151 offset:50176
	ds_read_b128 v[184:187], v151 offset:51200
	ds_read_b128 v[188:191], v151 offset:52224
	ds_read_b128 v[192:195], v151 offset:53248
	ds_read_b128 v[196:199], v151 offset:54272
	ds_read_b128 v[200:203], v151 offset:55296
	ds_read_b128 v[204:207], v151 offset:56320
	global_load_lds_dwordx4 v[208:209], off
	s_add_i32 m0, s22, 0x2000
	s_add_u32 s22, s34, 0x80080
	v_lshl_add_u64 v[208:209], v[210:211], 0, s[30:31]
	s_addc_u32 s23, s35, 0
	s_add_i32 s34, s90, s74
	global_load_lds_dwordx4 v[208:209], off
	v_lshl_add_u64 v[208:209], s[22:23], 0, v[0:1]
	s_mov_b32 m0, s34
	s_nop 0
	global_load_lds_dwordx4 v[208:209], off
	v_lshl_add_u64 v[208:209], s[22:23], 0, v[130:131]
	s_add_i32 m0, s34, 0x2000
	s_nop 0
	global_load_lds_dwordx4 v[208:209], off
	v_lshl_add_u64 v[208:209], v[216:217], 0, s[30:31]
	s_mov_b32 m0, s79
	s_nop 0
	global_load_lds_dwordx4 v[208:209], off
	v_lshl_add_u64 v[208:209], v[220:221], 0, s[30:31]
	s_mov_b32 m0, s80
	s_nop 0
	global_load_lds_dwordx4 v[208:209], off
	s_waitcnt vmcnt(8)
	s_waitcnt lgkmcnt(0)
	s_barrier
	s_waitcnt lgkmcnt(0)
	v_mfma_f32_16x16x32_bf16 v[62:65], v[140:143], v[176:179], v[62:65]
	v_mfma_f32_16x16x32_bf16 v[58:61], v[152:155], v[176:179], v[58:61]
	v_mfma_f32_16x16x32_bf16 v[50:53], v[140:143], v[184:187], v[50:53]
	v_mfma_f32_16x16x32_bf16 v[42:45], v[152:155], v[184:187], v[42:45]
	v_mfma_f32_16x16x32_bf16 v[34:37], v[140:143], v[192:195], v[34:37]
	v_mfma_f32_16x16x32_bf16 v[26:29], v[152:155], v[192:195], v[26:29]
	v_mfma_f32_16x16x32_bf16 v[14:17], v[140:143], v[200:203], v[14:17]
	v_mfma_f32_16x16x32_bf16 v[10:13], v[152:155], v[200:203], v[10:13]
	v_mfma_f32_16x16x32_bf16 v[62:65], v[144:147], v[180:183], v[62:65]
	v_mfma_f32_16x16x32_bf16 v[58:61], v[156:159], v[180:183], v[58:61]
	v_mfma_f32_16x16x32_bf16 v[50:53], v[144:147], v[188:191], v[50:53]
	v_mfma_f32_16x16x32_bf16 v[42:45], v[156:159], v[188:191], v[42:45]
	v_mfma_f32_16x16x32_bf16 v[34:37], v[144:147], v[196:199], v[34:37]
	v_mfma_f32_16x16x32_bf16 v[26:29], v[156:159], v[196:199], v[26:29]
	v_mfma_f32_16x16x32_bf16 v[14:17], v[144:147], v[204:207], v[14:17]
	v_mfma_f32_16x16x32_bf16 v[10:13], v[156:159], v[204:207], v[10:13]
	v_mfma_f32_16x16x32_bf16 v[54:57], v[160:163], v[176:179], v[54:57]
	v_mfma_f32_16x16x32_bf16 v[46:49], v[168:171], v[176:179], v[46:49]
	v_mfma_f32_16x16x32_bf16 v[38:41], v[160:163], v[184:187], v[38:41]
	v_mfma_f32_16x16x32_bf16 v[30:33], v[168:171], v[184:187], v[30:33]
	v_mfma_f32_16x16x32_bf16 v[22:25], v[160:163], v[192:195], v[22:25]
	v_mfma_f32_16x16x32_bf16 v[18:21], v[168:171], v[192:195], v[18:21]
	v_mfma_f32_16x16x32_bf16 v[6:9], v[160:163], v[200:203], v[6:9]
	v_mfma_f32_16x16x32_bf16 v[2:5], v[168:171], v[200:203], v[2:5]
	v_mfma_f32_16x16x32_bf16 v[54:57], v[164:167], v[180:183], v[54:57]
	v_mfma_f32_16x16x32_bf16 v[46:49], v[172:175], v[180:183], v[46:49]
	v_mfma_f32_16x16x32_bf16 v[38:41], v[164:167], v[188:191], v[38:41]
	v_mfma_f32_16x16x32_bf16 v[30:33], v[172:175], v[188:191], v[30:33]
	v_mfma_f32_16x16x32_bf16 v[22:25], v[164:167], v[196:199], v[22:25]
	v_mfma_f32_16x16x32_bf16 v[18:21], v[172:175], v[196:199], v[18:21]
	v_mfma_f32_16x16x32_bf16 v[6:9], v[164:167], v[204:207], v[6:9]
	v_mfma_f32_16x16x32_bf16 v[2:5], v[172:175], v[204:207], v[2:5]
	s_barrier
	s_add_i32 s88, s88, 2
	s_add_u32 s56, s56, 0x100
	s_addc_u32 s57, s57, 0
	s_add_u32 s86, s86, 0x100
	s_addc_u32 s87, s87, 0
	s_cmp_gt_u32 s88, 29
	s_cbranch_scc0 .LBB0_138
	s_and_b64 vcc, exec, s[42:43]
	s_cbranch_vccz .LBB0_141
	s_barrier

; #define PG8_STAGE(bufoff, gbase, voff) do { _Pragma("unroll") for (int _i = 0; _i < 2; ++_i) \
;         __builtin_amdgcn_global_load_lds((const unsigned*)((const char*)(gbase) + (voff)[_i]), (PG8_LAS unsigned*)(lds + (bufoff) + ldsw + _i * 8192), 16, 0, 0); } while (0)
; #define PG8_LDA(dst, b, h) do { _Pragma("unroll") for (int m = 0; m < 4; ++m) _Pragma("unroll") for (int k = 0; k < 2; ++k) dst[m][k] = *(const PG8_LAS bf16x8*)(lds + PG8_SA(b, h) + aoff + m * 2048 + k * 1024); } while (0)
; #define PG8_LDB(dst, b, h) do { _Pragma("unroll") for (int n = 0; n < 2; ++n) _Pragma("unroll") for (int k = 0; k < 2; ++k) dst[n][k] = *(const PG8_LAS bf16x8*)(lds + PG8_SB(b, h) + boff + n * 2048 + k * 1024); } while (0)
; #define PG8_MMA(ai, bj, At, Bt) do { __builtin_amdgcn_s_setprio(1); _Pragma("unroll") for (int m = 0; m < 4; ++m) _Pragma("unroll") for (int n = 0; n < 2; ++n) _Pragma("unroll") for (int k = 0; k < 2; ++k) \
;         acc[ai][bj][m][n] = __builtin_amdgcn_mfma_f32_16x16x32_bf16(Bt[n][k], At[m][k], acc[ai][bj][m][n], 0, 0, 0); __builtin_amdgcn_s_setprio(0); } while (0)
; #define PG8_WAIT_V(n) asm volatile("s_waitcnt vmcnt(" #n ")" ::: "memory")
; #define PG8_BAR __builtin_amdgcn_s_barrier()
; template <class Epi, class Sched, bool ALIGN_EPI = false, bool SP2 = false>
; __device__ __forceinline__ void gemm_phase(PG8_LAS unsigned char* lds, const Gemm g, const Sched& S, const Epi& E) {
;     ...
;         for (int t = 0; t < nt; t += 2) {
;             const bool last = (t == nt - 2);
;             const char* a1 = cA + (size_t)(t + 1) * kstep;
;             const char* a2 = last ? nA : cA + (size_t)(t + 2) * kstep; const char* b2 = last ? nB : cB + (size_t)(t + 2) * kstep;
;             const char* a3 = a2 + kstep; const char* b3 = b2 + kstep;
;             if (last && has_next) S.a_ready(nxt);
;             if constexpr (SP2) {
;             PG8_LDB(B0, 0, 0); PG8_LDB(B1, 0, 1); PG8_SCHED; PG8_LDA(At, 0, 0); PG8_STAGE(PG8_SA(1, 1), a1 + hstep, voffA);
;             PG8_WAIT_V(8); PG8_WAIT_L(0); PG8_BAR; PG8_MMA(0, 0, At, B0); PG8_MMA(0, 1, At, B1); PG8_BAR; PG8_SCHED;
;             PG8_LDA(At, 0, 1); PG8_STAGE(PG8_SB(0, 0), b2, voffB); PG8_STAGE(PG8_SB(0, 1), b2 + hstep, voffB); PG8_STAGE(PG8_SA(0, 0), a2, voffA);
;             PG8_WAIT_V(8); PG8_WAIT_L(0); PG8_BAR; PG8_MMA(1, 0, At, B0); PG8_MMA(1, 1, At, B1); PG8_BAR; PG8_SCHED;
.LBB0_571:
	s_add_u32 s22, s56, 0xfff80080
	s_addc_u32 s23, s57, -1
	s_add_i32 s89, 0, 0x10000
	s_cmp_eq_u32 s88, 28
	s_cselect_b32 s49, s47, s23
	s_cselect_b32 s48, s84, s22
	s_cselect_b32 s35, s45, s87
	s_cselect_b32 s34, s85, s86
	s_add_i32 s90, 0, 0x14000
	v_add_u32_e32 v156, s89, v141
	v_add_u32_e32 v172, s90, v141
	ds_read_b128 v[144:147], v156
	ds_read_b128 v[148:151], v156 offset:1024
	ds_read_b128 v[152:155], v156 offset:2048
	ds_read_b128 v[156:159], v156 offset:3072
	ds_read_b128 v[160:163], v172
	ds_read_b128 v[164:167], v172 offset:1024
	ds_read_b128 v[168:171], v172 offset:2048
	ds_read_b128 v[172:175], v172 offset:3072
	v_lshl_add_u64 v[208:209], s[56:57], 0, v[136:137]
	s_add_i32 m0, s75, 0xc000
	ds_read_b128 v[176:179], v143
	ds_read_b128 v[180:183], v143 offset:1024
	ds_read_b128 v[184:187], v143 offset:2048
	ds_read_b128 v[188:191], v143 offset:3072
	ds_read_b128 v[192:195], v143 offset:4096
	ds_read_b128 v[196:199], v143 offset:5120
	ds_read_b128 v[200:203], v143 offset:6144
	ds_read_b128 v[204:207], v143 offset:7168
	global_load_lds_dwordx4 v[208:209], off
	v_lshl_add_u64 v[208:209], s[56:57], 0, v[138:139]
	s_add_i32 m0, s75, 0xe000
	s_nop 0
	global_load_lds_dwordx4 v[208:209], off
	s_waitcnt vmcnt(8)
	s_waitcnt lgkmcnt(0)
	s_barrier
	s_waitcnt lgkmcnt(0)
	v_mfma_f32_16x16x32_bf16 v[126:129], v[144:147], v[176:179], v[126:129]
	v_mfma_f32_16x16x32_bf16 v[122:125], v[152:155], v[176:179], v[122:125]
	v_mfma_f32_16x16x32_bf16 v[118:121], v[144:147], v[184:187], v[118:121]
	v_mfma_f32_16x16x32_bf16 v[114:117], v[152:155], v[184:187], v[114:117]
	v_mfma_f32_16x16x32_bf16 v[102:105], v[144:147], v[192:195], v[102:105]
	v_mfma_f32_16x16x32_bf16 v[98:101], v[152:155], v[192:195], v[98:101]
	v_mfma_f32_16x16x32_bf16 v[86:89], v[144:147], v[200:203], v[86:89]
	v_mfma_f32_16x16x32_bf16 v[82:85], v[152:155], v[200:203], v[82:85]
	v_mfma_f32_16x16x32_bf16 v[126:129], v[148:151], v[180:183], v[126:129]
	v_mfma_f32_16x16x32_bf16 v[122:125], v[156:159], v[180:183], v[122:125]
	v_mfma_f32_16x16x32_bf16 v[118:121], v[148:151], v[188:191], v[118:121]
	v_mfma_f32_16x16x32_bf16 v[114:117], v[156:159], v[188:191], v[114:117]
	v_mfma_f32_16x16x32_bf16 v[102:105], v[148:151], v[196:199], v[102:105]
	v_mfma_f32_16x16x32_bf16 v[98:101], v[156:159], v[196:199], v[98:101]
	v_mfma_f32_16x16x32_bf16 v[86:89], v[148:151], v[204:207], v[86:89]
	v_mfma_f32_16x16x32_bf16 v[82:85], v[156:159], v[204:207], v[82:85]
	v_mfma_f32_16x16x32_bf16 v[110:113], v[160:163], v[176:179], v[110:113]
	v_mfma_f32_16x16x32_bf16 v[106:109], v[168:171], v[176:179], v[106:109]
	v_mfma_f32_16x16x32_bf16 v[94:97], v[160:163], v[184:187], v[94:97]
	v_mfma_f32_16x16x32_bf16 v[90:93], v[168:171], v[184:187], v[90:93]
	v_mfma_f32_16x16x32_bf16 v[78:81], v[160:163], v[192:195], v[78:81]
	v_mfma_f32_16x16x32_bf16 v[74:77], v[168:171], v[192:195], v[74:77]
	v_mfma_f32_16x16x32_bf16 v[70:73], v[160:163], v[200:203], v[70:73]
	v_mfma_f32_16x16x32_bf16 v[66:69], v[168:171], v[200:203], v[66:69]
	v_mfma_f32_16x16x32_bf16 v[110:113], v[164:167], v[180:183], v[110:113]
	v_mfma_f32_16x16x32_bf16 v[106:109], v[172:175], v[180:183], v[106:109]
	v_mfma_f32_16x16x32_bf16 v[94:97], v[164:167], v[188:191], v[94:97]
	v_mfma_f32_16x16x32_bf16 v[90:93], v[172:175], v[188:191], v[90:93]
	v_mfma_f32_16x16x32_bf16 v[78:81], v[164:167], v[196:199], v[78:81]
	v_mfma_f32_16x16x32_bf16 v[74:77], v[172:175], v[196:199], v[74:77]
	v_mfma_f32_16x16x32_bf16 v[70:73], v[164:167], v[204:207], v[70:73]
	v_mfma_f32_16x16x32_bf16 v[66:69], v[172:175], v[204:207], v[66:69]
	s_barrier
	s_add_i32 s22, s89, s74
	v_lshl_add_u64 v[208:209], s[34:35], 0, v[0:1]
	s_mov_b32 m0, s22
	ds_read_b128 v[176:179], v143 offset:16384
	ds_read_b128 v[180:183], v143 offset:17408
	ds_read_b128 v[184:187], v143 offset:18432
	ds_read_b128 v[188:191], v143 offset:19456
	ds_read_b128 v[192:195], v143 offset:20480
	ds_read_b128 v[196:199], v143 offset:21504
	ds_read_b128 v[200:203], v143 offset:22528
	ds_read_b128 v[204:207], v143 offset:23552
	global_load_lds_dwordx4 v[208:209], off
	s_add_i32 m0, s22, 0x2000
	s_add_u32 s22, s34, 0x80000
	v_lshl_add_u64 v[210:211], s[34:35], 0, v[130:131]
	s_addc_u32 s23, s35, 0
	s_add_i32 s89, s90, s74
	global_load_lds_dwordx4 v[210:211], off
	v_lshl_add_u64 v[216:217], s[22:23], 0, v[0:1]
	s_mov_b32 m0, s89
	v_lshl_add_u64 v[220:221], s[48:49], 0, v[132:133]
	global_load_lds_dwordx4 v[216:217], off
	v_lshl_add_u64 v[216:217], s[22:23], 0, v[130:131]
	s_add_i32 m0, s89, 0x2000
	s_nop 0
	global_load_lds_dwordx4 v[216:217], off
	v_lshl_add_u64 v[216:217], s[48:49], 0, v[134:135]
	s_mov_b32 m0, s75
	s_nop 0
	global_load_lds_dwordx4 v[216:217], off
	s_mov_b32 m0, s76
	s_nop 0
	global_load_lds_dwordx4 v[220:221], off
	s_waitcnt vmcnt(8)
	s_waitcnt lgkmcnt(0)
	s_barrier
; #define PG8_STAGE(bufoff, gbase, voff) do { _Pragma("unroll") for (int _i = 0; _i < 2; ++_i) \
;         __builtin_amdgcn_global_load_lds((const unsigned*)((const char*)(gbase) + (voff)[_i]), (PG8_LAS unsigned*)(lds + (bufoff) + ldsw + _i * 8192), 16, 0, 0); } while (0)
; #define PG8_LDA(dst, b, h) do { _Pragma("unroll") for (int m = 0; m < 4; ++m) _Pragma("unroll") for (int k = 0; k < 2; ++k) dst[m][k] = *(const PG8_LAS bf16x8*)(lds + PG8_SA(b, h) + aoff + m * 2048 + k * 1024); } while (0)
; #define PG8_LDB(dst, b, h) do { _Pragma("unroll") for (int n = 0; n < 2; ++n) _Pragma("unroll") for (int k = 0; k < 2; ++k) dst[n][k] = *(const PG8_LAS bf16x8*)(lds + PG8_SB(b, h) + boff + n * 2048 + k * 1024); } while (0)
; #define PG8_MMA(ai, bj, At, Bt) do { __builtin_amdgcn_s_setprio(1); _Pragma("unroll") for (int m = 0; m < 4; ++m) _Pragma("unroll") for (int n = 0; n < 2; ++n) _Pragma("unroll") for (int k = 0; k < 2; ++k) \
;         acc[ai][bj][m][n] = __builtin_amdgcn_mfma_f32_16x16x32_bf16(Bt[n][k], At[m][k], acc[ai][bj][m][n], 0, 0, 0); __builtin_amdgcn_s_setprio(0); } while (0)
; #define PG8_WAIT_V(n) asm volatile("s_waitcnt vmcnt(" #n ")" ::: "memory")
; #define PG8_WAIT_L(n) asm volatile("s_waitcnt lgkmcnt(" #n ")" ::: "memory")
; #define PG8_BAR __builtin_amdgcn_s_barrier()
; #define PG8_SCHED __builtin_amdgcn_sched_barrier(0)
; template <class Epi, class Sched, bool ALIGN_EPI = false, bool SP2 = false>
; __device__ __forceinline__ void gemm_phase(PG8_LAS unsigned char* lds, const Gemm g, const Sched& S, const Epi& E) {
;     ...
;             PG8_WAIT_V(8); PG8_WAIT_L(0); PG8_BAR; PG8_MMA(1, 0, At, B0); PG8_MMA(1, 1, At, B1); PG8_BAR; PG8_SCHED;
;             PG8_LDB(B0, 1, 0); PG8_LDB(B1, 1, 1); PG8_SCHED; PG8_LDA(At, 1, 0); PG8_STAGE(PG8_SA(0, 1), a2 + hstep, voffA);
;             PG8_WAIT_V(8); PG8_WAIT_L(0); PG8_BAR; PG8_MMA(0, 0, At, B0); PG8_MMA(0, 1, At, B1); PG8_BAR; PG8_SCHED;
;             PG8_LDA(At, 1, 1); PG8_STAGE(PG8_SB(1, 0), b3, voffB); PG8_STAGE(PG8_SB(1, 1), b3 + hstep, voffB); PG8_STAGE(PG8_SA(1, 0), a3, voffA);
	s_waitcnt lgkmcnt(0)
	v_mfma_f32_16x16x32_bf16 v[62:65], v[144:147], v[176:179], v[62:65]
	v_mfma_f32_16x16x32_bf16 v[58:61], v[152:155], v[176:179], v[58:61]
	v_mfma_f32_16x16x32_bf16 v[54:57], v[144:147], v[184:187], v[54:57]
	v_mfma_f32_16x16x32_bf16 v[50:53], v[152:155], v[184:187], v[50:53]
	v_mfma_f32_16x16x32_bf16 v[38:41], v[144:147], v[192:195], v[38:41]
	v_mfma_f32_16x16x32_bf16 v[34:37], v[152:155], v[192:195], v[34:37]
	v_mfma_f32_16x16x32_bf16 v[22:25], v[144:147], v[200:203], v[22:25]
	v_mfma_f32_16x16x32_bf16 v[18:21], v[152:155], v[200:203], v[18:21]
	v_mfma_f32_16x16x32_bf16 v[62:65], v[148:151], v[180:183], v[62:65]
	v_mfma_f32_16x16x32_bf16 v[58:61], v[156:159], v[180:183], v[58:61]
	v_mfma_f32_16x16x32_bf16 v[54:57], v[148:151], v[188:191], v[54:57]
	v_mfma_f32_16x16x32_bf16 v[50:53], v[156:159], v[188:191], v[50:53]
	v_mfma_f32_16x16x32_bf16 v[38:41], v[148:151], v[196:199], v[38:41]
	v_mfma_f32_16x16x32_bf16 v[34:37], v[156:159], v[196:199], v[34:37]
	v_mfma_f32_16x16x32_bf16 v[22:25], v[148:151], v[204:207], v[22:25]
	v_mfma_f32_16x16x32_bf16 v[18:21], v[156:159], v[204:207], v[18:21]
	v_mfma_f32_16x16x32_bf16 v[46:49], v[160:163], v[176:179], v[46:49]
	v_mfma_f32_16x16x32_bf16 v[42:45], v[168:171], v[176:179], v[42:45]
	v_mfma_f32_16x16x32_bf16 v[30:33], v[160:163], v[184:187], v[30:33]
	v_mfma_f32_16x16x32_bf16 v[26:29], v[168:171], v[184:187], v[26:29]
	v_mfma_f32_16x16x32_bf16 v[14:17], v[160:163], v[192:195], v[14:17]
	v_mfma_f32_16x16x32_bf16 v[10:13], v[168:171], v[192:195], v[10:13]
	v_mfma_f32_16x16x32_bf16 v[6:9], v[160:163], v[200:203], v[6:9]
	v_mfma_f32_16x16x32_bf16 v[2:5], v[168:171], v[200:203], v[2:5]
	v_mfma_f32_16x16x32_bf16 v[46:49], v[164:167], v[180:183], v[46:49]
	v_mfma_f32_16x16x32_bf16 v[42:45], v[172:175], v[180:183], v[42:45]
	v_mfma_f32_16x16x32_bf16 v[30:33], v[164:167], v[188:191], v[30:33]
	v_mfma_f32_16x16x32_bf16 v[26:29], v[172:175], v[188:191], v[26:29]
	v_mfma_f32_16x16x32_bf16 v[14:17], v[164:167], v[196:199], v[14:17]
	v_mfma_f32_16x16x32_bf16 v[10:13], v[172:175], v[196:199], v[10:13]
	v_mfma_f32_16x16x32_bf16 v[6:9], v[164:167], v[204:207], v[6:9]
	v_mfma_f32_16x16x32_bf16 v[2:5], v[172:175], v[204:207], v[2:5]
	s_barrier
	s_add_i32 s89, 0, 0x18000
	s_add_i32 s90, 0, 0x1c000
	v_add_u32_e32 v156, s89, v141
	v_add_u32_e32 v172, s90, v141
	ds_read_b128 v[144:147], v156
	ds_read_b128 v[148:151], v156 offset:1024
	ds_read_b128 v[152:155], v156 offset:2048
	ds_read_b128 v[156:159], v156 offset:3072
	ds_read_b128 v[160:163], v172
	ds_read_b128 v[164:167], v172 offset:1024
	ds_read_b128 v[168:171], v172 offset:2048
	ds_read_b128 v[172:175], v172 offset:3072
	s_add_u32 s22, s48, 0x80000
	s_addc_u32 s23, s49, 0
	s_mov_b32 m0, s77
	v_lshl_add_u64 v[222:223], s[22:23], 0, v[134:135]
	ds_read_b128 v[176:179], v143 offset:32768
	ds_read_b128 v[180:183], v143 offset:33792
	ds_read_b128 v[184:187], v143 offset:34816
	ds_read_b128 v[188:191], v143 offset:35840
	ds_read_b128 v[192:195], v143 offset:36864
	ds_read_b128 v[196:199], v143 offset:37888
	ds_read_b128 v[200:203], v143 offset:38912
	ds_read_b128 v[204:207], v143 offset:39936
	global_load_lds_dwordx4 v[222:223], off
	v_lshl_add_u64 v[222:223], s[22:23], 0, v[132:133]
	s_mov_b32 m0, s78
	s_nop 0
	global_load_lds_dwordx4 v[222:223], off
	s_waitcnt vmcnt(8)
	s_waitcnt lgkmcnt(0)
	s_barrier
	s_waitcnt lgkmcnt(0)
	v_mfma_f32_16x16x32_bf16 v[126:129], v[144:147], v[176:179], v[126:129]
	v_mfma_f32_16x16x32_bf16 v[122:125], v[152:155], v[176:179], v[122:125]
	v_mfma_f32_16x16x32_bf16 v[118:121], v[144:147], v[184:187], v[118:121]
	v_mfma_f32_16x16x32_bf16 v[114:117], v[152:155], v[184:187], v[114:117]
	v_mfma_f32_16x16x32_bf16 v[102:105], v[144:147], v[192:195], v[102:105]
	v_mfma_f32_16x16x32_bf16 v[98:101], v[152:155], v[192:195], v[98:101]
	v_mfma_f32_16x16x32_bf16 v[86:89], v[144:147], v[200:203], v[86:89]
	v_mfma_f32_16x16x32_bf16 v[82:85], v[152:155], v[200:203], v[82:85]
	v_mfma_f32_16x16x32_bf16 v[126:129], v[148:151], v[180:183], v[126:129]
	v_mfma_f32_16x16x32_bf16 v[122:125], v[156:159], v[180:183], v[122:125]
	v_mfma_f32_16x16x32_bf16 v[118:121], v[148:151], v[188:191], v[118:121]
	v_mfma_f32_16x16x32_bf16 v[114:117], v[156:159], v[188:191], v[114:117]
	v_mfma_f32_16x16x32_bf16 v[102:105], v[148:151], v[196:199], v[102:105]
	v_mfma_f32_16x16x32_bf16 v[98:101], v[156:159], v[196:199], v[98:101]
	v_mfma_f32_16x16x32_bf16 v[86:89], v[148:151], v[204:207], v[86:89]
	v_mfma_f32_16x16x32_bf16 v[82:85], v[156:159], v[204:207], v[82:85]
	v_mfma_f32_16x16x32_bf16 v[110:113], v[160:163], v[176:179], v[110:113]
	v_mfma_f32_16x16x32_bf16 v[106:109], v[168:171], v[176:179], v[106:109]
	v_mfma_f32_16x16x32_bf16 v[94:97], v[160:163], v[184:187], v[94:97]
	v_mfma_f32_16x16x32_bf16 v[90:93], v[168:171], v[184:187], v[90:93]
	v_mfma_f32_16x16x32_bf16 v[78:81], v[160:163], v[192:195], v[78:81]
	v_mfma_f32_16x16x32_bf16 v[74:77], v[168:171], v[192:195], v[74:77]
	v_mfma_f32_16x16x32_bf16 v[70:73], v[160:163], v[200:203], v[70:73]
	v_mfma_f32_16x16x32_bf16 v[66:69], v[168:171], v[200:203], v[66:69]
	v_mfma_f32_16x16x32_bf16 v[110:113], v[164:167], v[180:183], v[110:113]
	v_mfma_f32_16x16x32_bf16 v[106:109], v[172:175], v[180:183], v[106:109]
	v_mfma_f32_16x16x32_bf16 v[94:97], v[164:167], v[188:191], v[94:97]
	v_mfma_f32_16x16x32_bf16 v[90:93], v[172:175], v[188:191], v[90:93]
	v_mfma_f32_16x16x32_bf16 v[78:81], v[164:167], v[196:199], v[78:81]
	v_mfma_f32_16x16x32_bf16 v[74:77], v[172:175], v[196:199], v[74:77]
	v_mfma_f32_16x16x32_bf16 v[70:73], v[164:167], v[204:207], v[70:73]
	v_mfma_f32_16x16x32_bf16 v[66:69], v[172:175], v[204:207], v[66:69]
	s_barrier
; #define PG8_STAGE(bufoff, gbase, voff) do { _Pragma("unroll") for (int _i = 0; _i < 2; ++_i) \
;         __builtin_amdgcn_global_load_lds((const unsigned*)((const char*)(gbase) + (voff)[_i]), (PG8_LAS unsigned*)(lds + (bufoff) + ldsw + _i * 8192), 16, 0, 0); } while (0)
; #define PG8_LDA(dst, b, h) do { _Pragma("unroll") for (int m = 0; m < 4; ++m) _Pragma("unroll") for (int k = 0; k < 2; ++k) dst[m][k] = *(const PG8_LAS bf16x8*)(lds + PG8_SA(b, h) + aoff + m * 2048 + k * 1024); } while (0)
; #define PG8_MMA(ai, bj, At, Bt) do { __builtin_amdgcn_s_setprio(1); _Pragma("unroll") for (int m = 0; m < 4; ++m) _Pragma("unroll") for (int n = 0; n < 2; ++n) _Pragma("unroll") for (int k = 0; k < 2; ++k) \
;         acc[ai][bj][m][n] = __builtin_amdgcn_mfma_f32_16x16x32_bf16(Bt[n][k], At[m][k], acc[ai][bj][m][n], 0, 0, 0); __builtin_amdgcn_s_setprio(0); } while (0)
; #define PG8_WAIT_V(n) asm volatile("s_waitcnt vmcnt(" #n ")" ::: "memory")
; #define PG8_WAIT_L(n) asm volatile("s_waitcnt lgkmcnt(" #n ")" ::: "memory")
; #define PG8_BAR __builtin_amdgcn_s_barrier()
; #define PG8_SCHED __builtin_amdgcn_sched_barrier(0)
; template <class Epi, class Sched, bool ALIGN_EPI = false, bool SP2 = false>
; __device__ __forceinline__ void gemm_phase(PG8_LAS unsigned char* lds, const Gemm g, const Sched& S, const Epi& E) {
;     ...
;             PG8_LDA(At, 1, 1); PG8_STAGE(PG8_SB(1, 0), b3, voffB); PG8_STAGE(PG8_SB(1, 1), b3 + hstep, voffB); PG8_STAGE(PG8_SA(1, 0), a3, voffA);
;             PG8_WAIT_V(8); PG8_WAIT_L(0); PG8_BAR; PG8_MMA(1, 0, At, B0); PG8_MMA(1, 1, At, B1); PG8_BAR; PG8_SCHED;
	s_add_i32 s22, s89, s74
	v_lshl_add_u64 v[208:209], v[208:209], 0, s[30:31]
	s_mov_b32 m0, s22
	ds_read_b128 v[176:179], v143 offset:49152
	ds_read_b128 v[180:183], v143 offset:50176
	ds_read_b128 v[184:187], v143 offset:51200
	ds_read_b128 v[188:191], v143 offset:52224
	ds_read_b128 v[192:195], v143 offset:53248
	ds_read_b128 v[196:199], v143 offset:54272
	ds_read_b128 v[200:203], v143 offset:55296
	ds_read_b128 v[204:207], v143 offset:56320
	global_load_lds_dwordx4 v[208:209], off
	s_add_i32 m0, s22, 0x2000
	s_add_u32 s22, s34, 0x80080
	v_lshl_add_u64 v[208:209], v[210:211], 0, s[30:31]
	s_addc_u32 s23, s35, 0
	s_add_i32 s34, s90, s74
	global_load_lds_dwordx4 v[208:209], off
	v_lshl_add_u64 v[208:209], s[22:23], 0, v[0:1]
	s_mov_b32 m0, s34
	s_nop 0
	global_load_lds_dwordx4 v[208:209], off
	v_lshl_add_u64 v[208:209], s[22:23], 0, v[130:131]
	s_add_i32 m0, s34, 0x2000
	s_nop 0
	global_load_lds_dwordx4 v[208:209], off
	v_lshl_add_u64 v[208:209], v[216:217], 0, s[30:31]
	s_mov_b32 m0, s79
	s_nop 0
	global_load_lds_dwordx4 v[208:209], off
	v_lshl_add_u64 v[208:209], v[220:221], 0, s[30:31]
	s_mov_b32 m0, s80
	s_nop 0
	global_load_lds_dwordx4 v[208:209], off
	s_waitcnt vmcnt(8)
	s_waitcnt lgkmcnt(0)
	s_barrier
	s_waitcnt lgkmcnt(0)
	v_mfma_f32_16x16x32_bf16 v[62:65], v[144:147], v[176:179], v[62:65]
	v_mfma_f32_16x16x32_bf16 v[58:61], v[152:155], v[176:179], v[58:61]
	v_mfma_f32_16x16x32_bf16 v[54:57], v[144:147], v[184:187], v[54:57]
	v_mfma_f32_16x16x32_bf16 v[50:53], v[152:155], v[184:187], v[50:53]
	v_mfma_f32_16x16x32_bf16 v[38:41], v[144:147], v[192:195], v[38:41]
	v_mfma_f32_16x16x32_bf16 v[34:37], v[152:155], v[192:195], v[34:37]
	v_mfma_f32_16x16x32_bf16 v[22:25], v[144:147], v[200:203], v[22:25]
	v_mfma_f32_16x16x32_bf16 v[18:21], v[152:155], v[200:203], v[18:21]
	v_mfma_f32_16x16x32_bf16 v[62:65], v[148:151], v[180:183], v[62:65]
	v_mfma_f32_16x16x32_bf16 v[58:61], v[156:159], v[180:183], v[58:61]
	v_mfma_f32_16x16x32_bf16 v[54:57], v[148:151], v[188:191], v[54:57]
	v_mfma_f32_16x16x32_bf16 v[50:53], v[156:159], v[188:191], v[50:53]
	v_mfma_f32_16x16x32_bf16 v[38:41], v[148:151], v[196:199], v[38:41]
	v_mfma_f32_16x16x32_bf16 v[34:37], v[156:159], v[196:199], v[34:37]
	v_mfma_f32_16x16x32_bf16 v[22:25], v[148:151], v[204:207], v[22:25]
	v_mfma_f32_16x16x32_bf16 v[18:21], v[156:159], v[204:207], v[18:21]
	v_mfma_f32_16x16x32_bf16 v[46:49], v[160:163], v[176:179], v[46:49]
	v_mfma_f32_16x16x32_bf16 v[42:45], v[168:171], v[176:179], v[42:45]
	v_mfma_f32_16x16x32_bf16 v[30:33], v[160:163], v[184:187], v[30:33]
	v_mfma_f32_16x16x32_bf16 v[26:29], v[168:171], v[184:187], v[26:29]
	v_mfma_f32_16x16x32_bf16 v[14:17], v[160:163], v[192:195], v[14:17]
	v_mfma_f32_16x16x32_bf16 v[10:13], v[168:171], v[192:195], v[10:13]
	v_mfma_f32_16x16x32_bf16 v[6:9], v[160:163], v[200:203], v[6:9]
	v_mfma_f32_16x16x32_bf16 v[2:5], v[168:171], v[200:203], v[2:5]
	v_mfma_f32_16x16x32_bf16 v[46:49], v[164:167], v[180:183], v[46:49]
	v_mfma_f32_16x16x32_bf16 v[42:45], v[172:175], v[180:183], v[42:45]
	v_mfma_f32_16x16x32_bf16 v[30:33], v[164:167], v[188:191], v[30:33]
	v_mfma_f32_16x16x32_bf16 v[26:29], v[172:175], v[188:191], v[26:29]
	v_mfma_f32_16x16x32_bf16 v[14:17], v[164:167], v[196:199], v[14:17]
	v_mfma_f32_16x16x32_bf16 v[10:13], v[172:175], v[196:199], v[10:13]
	v_mfma_f32_16x16x32_bf16 v[6:9], v[164:167], v[204:207], v[6:9]
	v_mfma_f32_16x16x32_bf16 v[2:5], v[172:175], v[204:207], v[2:5]
	s_barrier
	s_add_i32 s88, s88, 2
	s_add_u32 s56, s56, 0x100
	s_addc_u32 s57, s57, 0
	s_add_u32 s86, s86, 0x100
	s_addc_u32 s87, s87, 0
	s_cmp_gt_u32 s88, 29
	s_cbranch_scc0 .LBB0_571
	s_and_b64 vcc, exec, s[42:43]
	s_cbranch_vccz .LBB0_574
	s_barrier

; #define PG8_STAGE(bufoff, gbase, voff) do { _Pragma("unroll") for (int _i = 0; _i < 2; ++_i) \
;         __builtin_amdgcn_global_load_lds((const unsigned*)((const char*)(gbase) + (voff)[_i]), (PG8_LAS unsigned*)(lds + (bufoff) + ldsw + _i * 8192), 16, 0, 0); } while (0)
; #define PG8_LDA(dst, b, h) do { _Pragma("unroll") for (int m = 0; m < 4; ++m) _Pragma("unroll") for (int k = 0; k < 2; ++k) dst[m][k] = *(const PG8_LAS bf16x8*)(lds + PG8_SA(b, h) + aoff + m * 2048 + k * 1024); } while (0)
; #define PG8_LDB(dst, b, h) do { _Pragma("unroll") for (int n = 0; n < 2; ++n) _Pragma("unroll") for (int k = 0; k < 2; ++k) dst[n][k] = *(const PG8_LAS bf16x8*)(lds + PG8_SB(b, h) + boff + n * 2048 + k * 1024); } while (0)
; #define PG8_MMA(ai, bj, At, Bt) do { __builtin_amdgcn_s_setprio(1); _Pragma("unroll") for (int m = 0; m < 4; ++m) _Pragma("unroll") for (int n = 0; n < 2; ++n) _Pragma("unroll") for (int k = 0; k < 2; ++k) \
;         acc[ai][bj][m][n] = __builtin_amdgcn_mfma_f32_16x16x32_bf16(Bt[n][k], At[m][k], acc[ai][bj][m][n], 0, 0, 0); __builtin_amdgcn_s_setprio(0); } while (0)
; #define PG8_WAIT_V(n) asm volatile("s_waitcnt vmcnt(" #n ")" ::: "memory")
; #define PG8_BAR __builtin_amdgcn_s_barrier()
; template <class Epi, class Sched, bool ALIGN_EPI = false, bool SP2 = false>
; __device__ __forceinline__ void gemm_phase(PG8_LAS unsigned char* lds, const Gemm g, const Sched& S, const Epi& E) {
;     ...
;         for (int t = 0; t < nt; t += 2) {
;             const bool last = (t == nt - 2);
;             const char* a1 = cA + (size_t)(t + 1) * kstep;
;             const char* a2 = last ? nA : cA + (size_t)(t + 2) * kstep; const char* b2 = last ? nB : cB + (size_t)(t + 2) * kstep;
;             const char* a3 = a2 + kstep; const char* b3 = b2 + kstep;
;             if (last && has_next) S.a_ready(nxt);
;             if constexpr (SP2) {
;             PG8_LDB(B0, 0, 0); PG8_LDB(B1, 0, 1); PG8_SCHED; PG8_LDA(At, 0, 0); PG8_STAGE(PG8_SA(1, 1), a1 + hstep, voffA);
;             PG8_WAIT_V(8); PG8_WAIT_L(0); PG8_BAR; PG8_MMA(0, 0, At, B0); PG8_MMA(0, 1, At, B1); PG8_BAR; PG8_SCHED;
;             PG8_LDA(At, 0, 1); PG8_STAGE(PG8_SB(0, 0), b2, voffB); PG8_STAGE(PG8_SB(0, 1), b2 + hstep, voffB); PG8_STAGE(PG8_SA(0, 0), a2, voffA);
;             PG8_WAIT_V(8); PG8_WAIT_L(0); PG8_BAR; PG8_MMA(1, 0, At, B0); PG8_MMA(1, 1, At, B1); PG8_BAR; PG8_SCHED;
.LBB0_704:
	s_add_u32 s22, s92, 0xfff80080
	s_addc_u32 s23, s93, -1
	s_add_i32 s89, 0, 0x10000
	s_cmp_eq_u32 s88, 28
	s_cselect_b32 s49, s51, s23
	s_cselect_b32 s48, s84, s22
	s_cselect_b32 s35, s47, s87
	s_cselect_b32 s34, s85, s86
	s_add_i32 s90, 0, 0x14000
	v_add_u32_e32 v156, s89, v149
	v_add_u32_e32 v172, s90, v149
	ds_read_b128 v[140:143], v156
	ds_read_b128 v[144:147], v156 offset:1024
	ds_read_b128 v[152:155], v156 offset:2048
	ds_read_b128 v[156:159], v156 offset:3072
	ds_read_b128 v[160:163], v172
	ds_read_b128 v[164:167], v172 offset:1024
	ds_read_b128 v[168:171], v172 offset:2048
	ds_read_b128 v[172:175], v172 offset:3072
	v_lshl_add_u64 v[208:209], s[92:93], 0, v[136:137]
	s_add_i32 m0, s75, 0xc000
	ds_read_b128 v[176:179], v151
	ds_read_b128 v[180:183], v151 offset:1024
	ds_read_b128 v[184:187], v151 offset:2048
	ds_read_b128 v[188:191], v151 offset:3072
	ds_read_b128 v[192:195], v151 offset:4096
	ds_read_b128 v[196:199], v151 offset:5120
	ds_read_b128 v[200:203], v151 offset:6144
	ds_read_b128 v[204:207], v151 offset:7168
	global_load_lds_dwordx4 v[208:209], off
	v_lshl_add_u64 v[208:209], s[92:93], 0, v[138:139]
	s_add_i32 m0, s75, 0xe000
	s_nop 0
	global_load_lds_dwordx4 v[208:209], off
	s_waitcnt vmcnt(8)
	s_waitcnt lgkmcnt(0)
	s_barrier
	s_waitcnt lgkmcnt(0)
	v_mfma_f32_16x16x32_bf16 v[126:129], v[140:143], v[176:179], v[126:129]
	v_mfma_f32_16x16x32_bf16 v[122:125], v[152:155], v[176:179], v[122:125]
	v_mfma_f32_16x16x32_bf16 v[110:113], v[140:143], v[184:187], v[110:113]
	v_mfma_f32_16x16x32_bf16 v[106:109], v[152:155], v[184:187], v[106:109]
	v_mfma_f32_16x16x32_bf16 v[94:97], v[140:143], v[192:195], v[94:97]
	v_mfma_f32_16x16x32_bf16 v[90:93], v[152:155], v[192:195], v[90:93]
	v_mfma_f32_16x16x32_bf16 v[78:81], v[140:143], v[200:203], v[78:81]
	v_mfma_f32_16x16x32_bf16 v[74:77], v[152:155], v[200:203], v[74:77]
	v_mfma_f32_16x16x32_bf16 v[126:129], v[144:147], v[180:183], v[126:129]
	v_mfma_f32_16x16x32_bf16 v[122:125], v[156:159], v[180:183], v[122:125]
	v_mfma_f32_16x16x32_bf16 v[110:113], v[144:147], v[188:191], v[110:113]
	v_mfma_f32_16x16x32_bf16 v[106:109], v[156:159], v[188:191], v[106:109]
	v_mfma_f32_16x16x32_bf16 v[94:97], v[144:147], v[196:199], v[94:97]
	v_mfma_f32_16x16x32_bf16 v[90:93], v[156:159], v[196:199], v[90:93]
	v_mfma_f32_16x16x32_bf16 v[78:81], v[144:147], v[204:207], v[78:81]
	v_mfma_f32_16x16x32_bf16 v[74:77], v[156:159], v[204:207], v[74:77]
	v_mfma_f32_16x16x32_bf16 v[118:121], v[160:163], v[176:179], v[118:121]
	v_mfma_f32_16x16x32_bf16 v[114:117], v[168:171], v[176:179], v[114:117]
	v_mfma_f32_16x16x32_bf16 v[102:105], v[160:163], v[184:187], v[102:105]
	v_mfma_f32_16x16x32_bf16 v[98:101], v[168:171], v[184:187], v[98:101]
	v_mfma_f32_16x16x32_bf16 v[86:89], v[160:163], v[192:195], v[86:89]
	v_mfma_f32_16x16x32_bf16 v[82:85], v[168:171], v[192:195], v[82:85]
	v_mfma_f32_16x16x32_bf16 v[70:73], v[160:163], v[200:203], v[70:73]
	v_mfma_f32_16x16x32_bf16 v[66:69], v[168:171], v[200:203], v[66:69]
	v_mfma_f32_16x16x32_bf16 v[118:121], v[164:167], v[180:183], v[118:121]
	v_mfma_f32_16x16x32_bf16 v[114:117], v[172:175], v[180:183], v[114:117]
	v_mfma_f32_16x16x32_bf16 v[102:105], v[164:167], v[188:191], v[102:105]
	v_mfma_f32_16x16x32_bf16 v[98:101], v[172:175], v[188:191], v[98:101]
	v_mfma_f32_16x16x32_bf16 v[86:89], v[164:167], v[196:199], v[86:89]
	v_mfma_f32_16x16x32_bf16 v[82:85], v[172:175], v[196:199], v[82:85]
	v_mfma_f32_16x16x32_bf16 v[70:73], v[164:167], v[204:207], v[70:73]
	v_mfma_f32_16x16x32_bf16 v[66:69], v[172:175], v[204:207], v[66:69]
	s_barrier
	s_add_i32 s22, s89, s74
	v_lshl_add_u64 v[208:209], s[34:35], 0, v[0:1]
	s_mov_b32 m0, s22
	ds_read_b128 v[176:179], v151 offset:16384
	ds_read_b128 v[180:183], v151 offset:17408
	ds_read_b128 v[184:187], v151 offset:18432
	ds_read_b128 v[188:191], v151 offset:19456
	ds_read_b128 v[192:195], v151 offset:20480
	ds_read_b128 v[196:199], v151 offset:21504
	ds_read_b128 v[200:203], v151 offset:22528
	ds_read_b128 v[204:207], v151 offset:23552
	global_load_lds_dwordx4 v[208:209], off
	s_add_i32 m0, s22, 0x2000
	s_add_u32 s22, s34, 0x80000
	v_lshl_add_u64 v[210:211], s[34:35], 0, v[130:131]
	s_addc_u32 s23, s35, 0
	s_add_i32 s89, s90, s74
	global_load_lds_dwordx4 v[210:211], off
	v_lshl_add_u64 v[216:217], s[22:23], 0, v[0:1]
	s_mov_b32 m0, s89
	v_lshl_add_u64 v[220:221], s[48:49], 0, v[132:133]
	global_load_lds_dwordx4 v[216:217], off
	v_lshl_add_u64 v[216:217], s[22:23], 0, v[130:131]
	s_add_i32 m0, s89, 0x2000
	s_nop 0
	global_load_lds_dwordx4 v[216:217], off
	v_lshl_add_u64 v[216:217], s[48:49], 0, v[134:135]
	s_mov_b32 m0, s75
	s_nop 0
	global_load_lds_dwordx4 v[216:217], off
	s_mov_b32 m0, s76
	s_nop 0
	global_load_lds_dwordx4 v[220:221], off
	s_waitcnt vmcnt(8)
	s_waitcnt lgkmcnt(0)
	s_barrier
; #define PG8_STAGE(bufoff, gbase, voff) do { _Pragma("unroll") for (int _i = 0; _i < 2; ++_i) \
;         __builtin_amdgcn_global_load_lds((const unsigned*)((const char*)(gbase) + (voff)[_i]), (PG8_LAS unsigned*)(lds + (bufoff) + ldsw + _i * 8192), 16, 0, 0); } while (0)
; #define PG8_LDA(dst, b, h) do { _Pragma("unroll") for (int m = 0; m < 4; ++m) _Pragma("unroll") for (int k = 0; k < 2; ++k) dst[m][k] = *(const PG8_LAS bf16x8*)(lds + PG8_SA(b, h) + aoff + m * 2048 + k * 1024); } while (0)
; #define PG8_LDB(dst, b, h) do { _Pragma("unroll") for (int n = 0; n < 2; ++n) _Pragma("unroll") for (int k = 0; k < 2; ++k) dst[n][k] = *(const PG8_LAS bf16x8*)(lds + PG8_SB(b, h) + boff + n * 2048 + k * 1024); } while (0)
; #define PG8_MMA(ai, bj, At, Bt) do { __builtin_amdgcn_s_setprio(1); _Pragma("unroll") for (int m = 0; m < 4; ++m) _Pragma("unroll") for (int n = 0; n < 2; ++n) _Pragma("unroll") for (int k = 0; k < 2; ++k) \
;         acc[ai][bj][m][n] = __builtin_amdgcn_mfma_f32_16x16x32_bf16(Bt[n][k], At[m][k], acc[ai][bj][m][n], 0, 0, 0); __builtin_amdgcn_s_setprio(0); } while (0)
; #define PG8_WAIT_V(n) asm volatile("s_waitcnt vmcnt(" #n ")" ::: "memory")
; #define PG8_WAIT_L(n) asm volatile("s_waitcnt lgkmcnt(" #n ")" ::: "memory")
; #define PG8_BAR __builtin_amdgcn_s_barrier()
; #define PG8_SCHED __builtin_amdgcn_sched_barrier(0)
; template <class Epi, class Sched, bool ALIGN_EPI = false, bool SP2 = false>
; __device__ __forceinline__ void gemm_phase(PG8_LAS unsigned char* lds, const Gemm g, const Sched& S, const Epi& E) {
;     ...
;             PG8_WAIT_V(8); PG8_WAIT_L(0); PG8_BAR; PG8_MMA(1, 0, At, B0); PG8_MMA(1, 1, At, B1); PG8_BAR; PG8_SCHED;
;             PG8_LDB(B0, 1, 0); PG8_LDB(B1, 1, 1); PG8_SCHED; PG8_LDA(At, 1, 0); PG8_STAGE(PG8_SA(0, 1), a2 + hstep, voffA);
;             PG8_WAIT_V(8); PG8_WAIT_L(0); PG8_BAR; PG8_MMA(0, 0, At, B0); PG8_MMA(0, 1, At, B1); PG8_BAR; PG8_SCHED;
;             PG8_LDA(At, 1, 1); PG8_STAGE(PG8_SB(1, 0), b3, voffB); PG8_STAGE(PG8_SB(1, 1), b3 + hstep, voffB); PG8_STAGE(PG8_SA(1, 0), a3, voffA);
	s_waitcnt lgkmcnt(0)
	v_mfma_f32_16x16x32_bf16 v[62:65], v[140:143], v[176:179], v[62:65]
	v_mfma_f32_16x16x32_bf16 v[58:61], v[152:155], v[176:179], v[58:61]
	v_mfma_f32_16x16x32_bf16 v[46:49], v[140:143], v[184:187], v[46:49]
	v_mfma_f32_16x16x32_bf16 v[42:45], v[152:155], v[184:187], v[42:45]
	v_mfma_f32_16x16x32_bf16 v[30:33], v[140:143], v[192:195], v[30:33]
	v_mfma_f32_16x16x32_bf16 v[26:29], v[152:155], v[192:195], v[26:29]
	v_mfma_f32_16x16x32_bf16 v[14:17], v[140:143], v[200:203], v[14:17]
	v_mfma_f32_16x16x32_bf16 v[10:13], v[152:155], v[200:203], v[10:13]
	v_mfma_f32_16x16x32_bf16 v[62:65], v[144:147], v[180:183], v[62:65]
	v_mfma_f32_16x16x32_bf16 v[58:61], v[156:159], v[180:183], v[58:61]
	v_mfma_f32_16x16x32_bf16 v[46:49], v[144:147], v[188:191], v[46:49]
	v_mfma_f32_16x16x32_bf16 v[42:45], v[156:159], v[188:191], v[42:45]
	v_mfma_f32_16x16x32_bf16 v[30:33], v[144:147], v[196:199], v[30:33]
	v_mfma_f32_16x16x32_bf16 v[26:29], v[156:159], v[196:199], v[26:29]
	v_mfma_f32_16x16x32_bf16 v[14:17], v[144:147], v[204:207], v[14:17]
	v_mfma_f32_16x16x32_bf16 v[10:13], v[156:159], v[204:207], v[10:13]
	v_mfma_f32_16x16x32_bf16 v[54:57], v[160:163], v[176:179], v[54:57]
	v_mfma_f32_16x16x32_bf16 v[50:53], v[168:171], v[176:179], v[50:53]
	v_mfma_f32_16x16x32_bf16 v[38:41], v[160:163], v[184:187], v[38:41]
	v_mfma_f32_16x16x32_bf16 v[34:37], v[168:171], v[184:187], v[34:37]
	v_mfma_f32_16x16x32_bf16 v[22:25], v[160:163], v[192:195], v[22:25]
	v_mfma_f32_16x16x32_bf16 v[18:21], v[168:171], v[192:195], v[18:21]
	v_mfma_f32_16x16x32_bf16 v[6:9], v[160:163], v[200:203], v[6:9]
	v_mfma_f32_16x16x32_bf16 v[2:5], v[168:171], v[200:203], v[2:5]
	v_mfma_f32_16x16x32_bf16 v[54:57], v[164:167], v[180:183], v[54:57]
	v_mfma_f32_16x16x32_bf16 v[50:53], v[172:175], v[180:183], v[50:53]
	v_mfma_f32_16x16x32_bf16 v[38:41], v[164:167], v[188:191], v[38:41]
	v_mfma_f32_16x16x32_bf16 v[34:37], v[172:175], v[188:191], v[34:37]
	v_mfma_f32_16x16x32_bf16 v[22:25], v[164:167], v[196:199], v[22:25]
	v_mfma_f32_16x16x32_bf16 v[18:21], v[172:175], v[196:199], v[18:21]
	v_mfma_f32_16x16x32_bf16 v[6:9], v[164:167], v[204:207], v[6:9]
	v_mfma_f32_16x16x32_bf16 v[2:5], v[172:175], v[204:207], v[2:5]
	s_barrier
	s_add_i32 s89, 0, 0x18000
	s_add_i32 s90, 0, 0x1c000
	v_add_u32_e32 v156, s89, v149
	v_add_u32_e32 v172, s90, v149
	ds_read_b128 v[140:143], v156
	ds_read_b128 v[144:147], v156 offset:1024
	ds_read_b128 v[152:155], v156 offset:2048
	ds_read_b128 v[156:159], v156 offset:3072
	ds_read_b128 v[160:163], v172
	ds_read_b128 v[164:167], v172 offset:1024
	ds_read_b128 v[168:171], v172 offset:2048
	ds_read_b128 v[172:175], v172 offset:3072
	s_add_u32 s22, s48, 0x80000
	s_addc_u32 s23, s49, 0
	s_mov_b32 m0, s77
	v_lshl_add_u64 v[222:223], s[22:23], 0, v[134:135]
	ds_read_b128 v[176:179], v151 offset:32768
	ds_read_b128 v[180:183], v151 offset:33792
	ds_read_b128 v[184:187], v151 offset:34816
	ds_read_b128 v[188:191], v151 offset:35840
	ds_read_b128 v[192:195], v151 offset:36864
	ds_read_b128 v[196:199], v151 offset:37888
	ds_read_b128 v[200:203], v151 offset:38912
	ds_read_b128 v[204:207], v151 offset:39936
	global_load_lds_dwordx4 v[222:223], off
	v_lshl_add_u64 v[222:223], s[22:23], 0, v[132:133]
	s_mov_b32 m0, s78
	s_nop 0
	global_load_lds_dwordx4 v[222:223], off
	s_waitcnt vmcnt(8)
	s_waitcnt lgkmcnt(0)
	s_barrier
	s_waitcnt lgkmcnt(0)
	v_mfma_f32_16x16x32_bf16 v[126:129], v[140:143], v[176:179], v[126:129]
	v_mfma_f32_16x16x32_bf16 v[122:125], v[152:155], v[176:179], v[122:125]
	v_mfma_f32_16x16x32_bf16 v[110:113], v[140:143], v[184:187], v[110:113]
	v_mfma_f32_16x16x32_bf16 v[106:109], v[152:155], v[184:187], v[106:109]
	v_mfma_f32_16x16x32_bf16 v[94:97], v[140:143], v[192:195], v[94:97]
	v_mfma_f32_16x16x32_bf16 v[90:93], v[152:155], v[192:195], v[90:93]
	v_mfma_f32_16x16x32_bf16 v[78:81], v[140:143], v[200:203], v[78:81]
	v_mfma_f32_16x16x32_bf16 v[74:77], v[152:155], v[200:203], v[74:77]
	v_mfma_f32_16x16x32_bf16 v[126:129], v[144:147], v[180:183], v[126:129]
	v_mfma_f32_16x16x32_bf16 v[122:125], v[156:159], v[180:183], v[122:125]
	v_mfma_f32_16x16x32_bf16 v[110:113], v[144:147], v[188:191], v[110:113]
	v_mfma_f32_16x16x32_bf16 v[106:109], v[156:159], v[188:191], v[106:109]
	v_mfma_f32_16x16x32_bf16 v[94:97], v[144:147], v[196:199], v[94:97]
	v_mfma_f32_16x16x32_bf16 v[90:93], v[156:159], v[196:199], v[90:93]
	v_mfma_f32_16x16x32_bf16 v[78:81], v[144:147], v[204:207], v[78:81]
	v_mfma_f32_16x16x32_bf16 v[74:77], v[156:159], v[204:207], v[74:77]
	v_mfma_f32_16x16x32_bf16 v[118:121], v[160:163], v[176:179], v[118:121]
	v_mfma_f32_16x16x32_bf16 v[114:117], v[168:171], v[176:179], v[114:117]
	v_mfma_f32_16x16x32_bf16 v[102:105], v[160:163], v[184:187], v[102:105]
	v_mfma_f32_16x16x32_bf16 v[98:101], v[168:171], v[184:187], v[98:101]
	v_mfma_f32_16x16x32_bf16 v[86:89], v[160:163], v[192:195], v[86:89]
	v_mfma_f32_16x16x32_bf16 v[82:85], v[168:171], v[192:195], v[82:85]
	v_mfma_f32_16x16x32_bf16 v[70:73], v[160:163], v[200:203], v[70:73]
	v_mfma_f32_16x16x32_bf16 v[66:69], v[168:171], v[200:203], v[66:69]
	v_mfma_f32_16x16x32_bf16 v[118:121], v[164:167], v[180:183], v[118:121]
	v_mfma_f32_16x16x32_bf16 v[114:117], v[172:175], v[180:183], v[114:117]
	v_mfma_f32_16x16x32_bf16 v[102:105], v[164:167], v[188:191], v[102:105]
	v_mfma_f32_16x16x32_bf16 v[98:101], v[172:175], v[188:191], v[98:101]
	v_mfma_f32_16x16x32_bf16 v[86:89], v[164:167], v[196:199], v[86:89]
	v_mfma_f32_16x16x32_bf16 v[82:85], v[172:175], v[196:199], v[82:85]
	v_mfma_f32_16x16x32_bf16 v[70:73], v[164:167], v[204:207], v[70:73]
	v_mfma_f32_16x16x32_bf16 v[66:69], v[172:175], v[204:207], v[66:69]
	s_barrier
; #define PG8_STAGE(bufoff, gbase, voff) do { _Pragma("unroll") for (int _i = 0; _i < 2; ++_i) \
;         __builtin_amdgcn_global_load_lds((const unsigned*)((const char*)(gbase) + (voff)[_i]), (PG8_LAS unsigned*)(lds + (bufoff) + ldsw + _i * 8192), 16, 0, 0); } while (0)
; #define PG8_LDA(dst, b, h) do { _Pragma("unroll") for (int m = 0; m < 4; ++m) _Pragma("unroll") for (int k = 0; k < 2; ++k) dst[m][k] = *(const PG8_LAS bf16x8*)(lds + PG8_SA(b, h) + aoff + m * 2048 + k * 1024); } while (0)
; #define PG8_MMA(ai, bj, At, Bt) do { __builtin_amdgcn_s_setprio(1); _Pragma("unroll") for (int m = 0; m < 4; ++m) _Pragma("unroll") for (int n = 0; n < 2; ++n) _Pragma("unroll") for (int k = 0; k < 2; ++k) \
;         acc[ai][bj][m][n] = __builtin_amdgcn_mfma_f32_16x16x32_bf16(Bt[n][k], At[m][k], acc[ai][bj][m][n], 0, 0, 0); __builtin_amdgcn_s_setprio(0); } while (0)
; #define PG8_WAIT_V(n) asm volatile("s_waitcnt vmcnt(" #n ")" ::: "memory")
; #define PG8_WAIT_L(n) asm volatile("s_waitcnt lgkmcnt(" #n ")" ::: "memory")
; #define PG8_BAR __builtin_amdgcn_s_barrier()
; #define PG8_SCHED __builtin_amdgcn_sched_barrier(0)
; template <class Epi, class Sched, bool ALIGN_EPI = false, bool SP2 = false>
; __device__ __forceinline__ void gemm_phase(PG8_LAS unsigned char* lds, const Gemm g, const Sched& S, const Epi& E) {
;     ...
;             PG8_LDA(At, 1, 1); PG8_STAGE(PG8_SB(1, 0), b3, voffB); PG8_STAGE(PG8_SB(1, 1), b3 + hstep, voffB); PG8_STAGE(PG8_SA(1, 0), a3, voffA);
;             PG8_WAIT_V(8); PG8_WAIT_L(0); PG8_BAR; PG8_MMA(1, 0, At, B0); PG8_MMA(1, 1, At, B1); PG8_BAR; PG8_SCHED;
	s_add_i32 s22, s89, s74
	v_lshl_add_u64 v[208:209], v[208:209], 0, s[30:31]
	s_mov_b32 m0, s22
	ds_read_b128 v[176:179], v151 offset:49152
	ds_read_b128 v[180:183], v151 offset:50176
	ds_read_b128 v[184:187], v151 offset:51200
	ds_read_b128 v[188:191], v151 offset:52224
	ds_read_b128 v[192:195], v151 offset:53248
	ds_read_b128 v[196:199], v151 offset:54272
	ds_read_b128 v[200:203], v151 offset:55296
	ds_read_b128 v[204:207], v151 offset:56320
	global_load_lds_dwordx4 v[208:209], off
	s_add_i32 m0, s22, 0x2000
	s_add_u32 s22, s34, 0x80080
	v_lshl_add_u64 v[208:209], v[210:211], 0, s[30:31]
	s_addc_u32 s23, s35, 0
	s_add_i32 s34, s90, s74
	global_load_lds_dwordx4 v[208:209], off
	v_lshl_add_u64 v[208:209], s[22:23], 0, v[0:1]
	s_mov_b32 m0, s34
	s_nop 0
	global_load_lds_dwordx4 v[208:209], off
	v_lshl_add_u64 v[208:209], s[22:23], 0, v[130:131]
	s_add_i32 m0, s34, 0x2000
	s_nop 0
	global_load_lds_dwordx4 v[208:209], off
	v_lshl_add_u64 v[208:209], v[216:217], 0, s[30:31]
	s_mov_b32 m0, s79
	s_nop 0
	global_load_lds_dwordx4 v[208:209], off
	v_lshl_add_u64 v[208:209], v[220:221], 0, s[30:31]
	s_mov_b32 m0, s80
	s_nop 0
	global_load_lds_dwordx4 v[208:209], off
	s_waitcnt vmcnt(8)
	s_waitcnt lgkmcnt(0)
	s_barrier
	s_waitcnt lgkmcnt(0)
	v_mfma_f32_16x16x32_bf16 v[62:65], v[140:143], v[176:179], v[62:65]
	v_mfma_f32_16x16x32_bf16 v[58:61], v[152:155], v[176:179], v[58:61]
	v_mfma_f32_16x16x32_bf16 v[46:49], v[140:143], v[184:187], v[46:49]
	v_mfma_f32_16x16x32_bf16 v[42:45], v[152:155], v[184:187], v[42:45]
	v_mfma_f32_16x16x32_bf16 v[30:33], v[140:143], v[192:195], v[30:33]
	v_mfma_f32_16x16x32_bf16 v[26:29], v[152:155], v[192:195], v[26:29]
	v_mfma_f32_16x16x32_bf16 v[14:17], v[140:143], v[200:203], v[14:17]
	v_mfma_f32_16x16x32_bf16 v[10:13], v[152:155], v[200:203], v[10:13]
	v_mfma_f32_16x16x32_bf16 v[62:65], v[144:147], v[180:183], v[62:65]
	v_mfma_f32_16x16x32_bf16 v[58:61], v[156:159], v[180:183], v[58:61]
	v_mfma_f32_16x16x32_bf16 v[46:49], v[144:147], v[188:191], v[46:49]
	v_mfma_f32_16x16x32_bf16 v[42:45], v[156:159], v[188:191], v[42:45]
	v_mfma_f32_16x16x32_bf16 v[30:33], v[144:147], v[196:199], v[30:33]
	v_mfma_f32_16x16x32_bf16 v[26:29], v[156:159], v[196:199], v[26:29]
	v_mfma_f32_16x16x32_bf16 v[14:17], v[144:147], v[204:207], v[14:17]
	v_mfma_f32_16x16x32_bf16 v[10:13], v[156:159], v[204:207], v[10:13]
	v_mfma_f32_16x16x32_bf16 v[54:57], v[160:163], v[176:179], v[54:57]
	v_mfma_f32_16x16x32_bf16 v[50:53], v[168:171], v[176:179], v[50:53]
	v_mfma_f32_16x16x32_bf16 v[38:41], v[160:163], v[184:187], v[38:41]
	v_mfma_f32_16x16x32_bf16 v[34:37], v[168:171], v[184:187], v[34:37]
	v_mfma_f32_16x16x32_bf16 v[22:25], v[160:163], v[192:195], v[22:25]
	v_mfma_f32_16x16x32_bf16 v[18:21], v[168:171], v[192:195], v[18:21]
	v_mfma_f32_16x16x32_bf16 v[6:9], v[160:163], v[200:203], v[6:9]
	v_mfma_f32_16x16x32_bf16 v[2:5], v[168:171], v[200:203], v[2:5]
	v_mfma_f32_16x16x32_bf16 v[54:57], v[164:167], v[180:183], v[54:57]
	v_mfma_f32_16x16x32_bf16 v[50:53], v[172:175], v[180:183], v[50:53]
	v_mfma_f32_16x16x32_bf16 v[38:41], v[164:167], v[188:191], v[38:41]
	v_mfma_f32_16x16x32_bf16 v[34:37], v[172:175], v[188:191], v[34:37]
	v_mfma_f32_16x16x32_bf16 v[22:25], v[164:167], v[196:199], v[22:25]
	v_mfma_f32_16x16x32_bf16 v[18:21], v[172:175], v[196:199], v[18:21]
	v_mfma_f32_16x16x32_bf16 v[6:9], v[164:167], v[204:207], v[6:9]
	v_mfma_f32_16x16x32_bf16 v[2:5], v[172:175], v[204:207], v[2:5]
	s_barrier
	s_add_i32 s88, s88, 2
	s_add_u32 s92, s92, 0x100
	s_addc_u32 s93, s93, 0
	s_add_u32 s86, s86, 0x100
	s_addc_u32 s87, s87, 0
	s_cmp_gt_u32 s88, 29
	s_cbranch_scc0 .LBB0_704
	s_and_b64 vcc, exec, s[44:45]
	s_cbranch_vccz .LBB0_707
	s_barrier

; #define PG8_STAGE(bufoff, gbase, voff) do { _Pragma("unroll") for (int _i = 0; _i < 2; ++_i) \
;         __builtin_amdgcn_global_load_lds((const unsigned*)((const char*)(gbase) + (voff)[_i]), (PG8_LAS unsigned*)(lds + (bufoff) + ldsw + _i * 8192), 16, 0, 0); } while (0)
; #define PG8_LDA(dst, b, h) do { _Pragma("unroll") for (int m = 0; m < 4; ++m) _Pragma("unroll") for (int k = 0; k < 2; ++k) dst[m][k] = *(const PG8_LAS bf16x8*)(lds + PG8_SA(b, h) + aoff + m * 2048 + k * 1024); } while (0)
; #define PG8_LDB(dst, b, h) do { _Pragma("unroll") for (int n = 0; n < 2; ++n) _Pragma("unroll") for (int k = 0; k < 2; ++k) dst[n][k] = *(const PG8_LAS bf16x8*)(lds + PG8_SB(b, h) + boff + n * 2048 + k * 1024); } while (0)
; #define PG8_MMA(ai, bj, At, Bt) do { __builtin_amdgcn_s_setprio(1); _Pragma("unroll") for (int m = 0; m < 4; ++m) _Pragma("unroll") for (int n = 0; n < 2; ++n) _Pragma("unroll") for (int k = 0; k < 2; ++k) \
;         acc[ai][bj][m][n] = __builtin_amdgcn_mfma_f32_16x16x32_bf16(Bt[n][k], At[m][k], acc[ai][bj][m][n], 0, 0, 0); __builtin_amdgcn_s_setprio(0); } while (0)
; #define PG8_WAIT_V(n) asm volatile("s_waitcnt vmcnt(" #n ")" ::: "memory")
; #define PG8_BAR __builtin_amdgcn_s_barrier()
; template <class Epi, class Sched, bool ALIGN_EPI = false, bool SP2 = false>
; __device__ __forceinline__ void gemm_phase(PG8_LAS unsigned char* lds, const Gemm g, const Sched& S, const Epi& E) {
;     ...
;         for (int t = 0; t < nt; t += 2) {
;             const bool last = (t == nt - 2);
;             const char* a1 = cA + (size_t)(t + 1) * kstep;
;             const char* a2 = last ? nA : cA + (size_t)(t + 2) * kstep; const char* b2 = last ? nB : cB + (size_t)(t + 2) * kstep;
;             const char* a3 = a2 + kstep; const char* b3 = b2 + kstep;
;             if (last && has_next) S.a_ready(nxt);
;             if constexpr (SP2) {
;             PG8_LDB(B0, 0, 0); PG8_LDB(B1, 0, 1); PG8_SCHED; PG8_LDA(At, 0, 0); PG8_STAGE(PG8_SA(1, 1), a1 + hstep, voffA);
;             PG8_WAIT_V(8); PG8_WAIT_L(0); PG8_BAR; PG8_MMA(0, 0, At, B0); PG8_MMA(0, 1, At, B1); PG8_BAR; PG8_SCHED;
;             PG8_LDA(At, 0, 1); PG8_STAGE(PG8_SB(0, 0), b2, voffB); PG8_STAGE(PG8_SB(0, 1), b2 + hstep, voffB); PG8_STAGE(PG8_SA(0, 0), a2, voffA);
;             PG8_WAIT_V(8); PG8_WAIT_L(0); PG8_BAR; PG8_MMA(1, 0, At, B0); PG8_MMA(1, 1, At, B1); PG8_BAR; PG8_SCHED;
.LBB0_783:
	s_add_u32 s34, s46, 0x100
	s_addc_u32 s35, s47, 0
	s_add_i32 s22, 0, 0x10000
	s_cmpk_eq_i32 s84, 0x54
	s_cselect_b32 s51, s41, s35
	s_cselect_b32 s50, s40, s34
	s_cselect_b32 s49, s45, s83
	s_cselect_b32 s48, s44, s82
	s_add_i32 s85, 0, 0x14000
	v_add_u32_e32 v156, s22, v141
	v_add_u32_e32 v172, s85, v141
	ds_read_b128 v[144:147], v156
	ds_read_b128 v[148:151], v156 offset:1024
	ds_read_b128 v[152:155], v156 offset:2048
	ds_read_b128 v[156:159], v156 offset:3072
	ds_read_b128 v[160:163], v172
	ds_read_b128 v[164:167], v172 offset:1024
	ds_read_b128 v[168:171], v172 offset:2048
	ds_read_b128 v[172:175], v172 offset:3072
	v_lshl_add_u64 v[208:209], s[46:47], 0, v[136:137]
	s_add_i32 m0, s57, 0xc000
	ds_read_b128 v[176:179], v143
	ds_read_b128 v[180:183], v143 offset:1024
	ds_read_b128 v[184:187], v143 offset:2048
	ds_read_b128 v[188:191], v143 offset:3072
	ds_read_b128 v[192:195], v143 offset:4096
	ds_read_b128 v[196:199], v143 offset:5120
	ds_read_b128 v[200:203], v143 offset:6144
	ds_read_b128 v[204:207], v143 offset:7168
	global_load_lds_dwordx4 v[208:209], off
	v_lshl_add_u64 v[208:209], s[46:47], 0, v[138:139]
	s_add_i32 m0, s57, 0xe000
	s_nop 0
	global_load_lds_dwordx4 v[208:209], off
	s_waitcnt vmcnt(8)
	s_waitcnt lgkmcnt(0)
	s_barrier
	s_waitcnt lgkmcnt(0)
	v_mfma_f32_16x16x32_bf16 v[126:129], v[144:147], v[176:179], v[126:129]
	v_mfma_f32_16x16x32_bf16 v[122:125], v[152:155], v[176:179], v[122:125]
	v_mfma_f32_16x16x32_bf16 v[118:121], v[144:147], v[184:187], v[118:121]
	v_mfma_f32_16x16x32_bf16 v[114:117], v[152:155], v[184:187], v[114:117]
	v_mfma_f32_16x16x32_bf16 v[102:105], v[144:147], v[192:195], v[102:105]
	v_mfma_f32_16x16x32_bf16 v[98:101], v[152:155], v[192:195], v[98:101]
	v_mfma_f32_16x16x32_bf16 v[86:89], v[144:147], v[200:203], v[86:89]
	v_mfma_f32_16x16x32_bf16 v[82:85], v[152:155], v[200:203], v[82:85]
	v_mfma_f32_16x16x32_bf16 v[126:129], v[148:151], v[180:183], v[126:129]
	v_mfma_f32_16x16x32_bf16 v[122:125], v[156:159], v[180:183], v[122:125]
	v_mfma_f32_16x16x32_bf16 v[118:121], v[148:151], v[188:191], v[118:121]
	v_mfma_f32_16x16x32_bf16 v[114:117], v[156:159], v[188:191], v[114:117]
	v_mfma_f32_16x16x32_bf16 v[102:105], v[148:151], v[196:199], v[102:105]
	v_mfma_f32_16x16x32_bf16 v[98:101], v[156:159], v[196:199], v[98:101]
	v_mfma_f32_16x16x32_bf16 v[86:89], v[148:151], v[204:207], v[86:89]
	v_mfma_f32_16x16x32_bf16 v[82:85], v[156:159], v[204:207], v[82:85]
	v_mfma_f32_16x16x32_bf16 v[110:113], v[160:163], v[176:179], v[110:113]
	v_mfma_f32_16x16x32_bf16 v[106:109], v[168:171], v[176:179], v[106:109]
	v_mfma_f32_16x16x32_bf16 v[94:97], v[160:163], v[184:187], v[94:97]
	v_mfma_f32_16x16x32_bf16 v[90:93], v[168:171], v[184:187], v[90:93]
	v_mfma_f32_16x16x32_bf16 v[78:81], v[160:163], v[192:195], v[78:81]
	v_mfma_f32_16x16x32_bf16 v[74:77], v[168:171], v[192:195], v[74:77]
	v_mfma_f32_16x16x32_bf16 v[70:73], v[160:163], v[200:203], v[70:73]
	v_mfma_f32_16x16x32_bf16 v[66:69], v[168:171], v[200:203], v[66:69]
	v_mfma_f32_16x16x32_bf16 v[110:113], v[164:167], v[180:183], v[110:113]
	v_mfma_f32_16x16x32_bf16 v[106:109], v[172:175], v[180:183], v[106:109]
	v_mfma_f32_16x16x32_bf16 v[94:97], v[164:167], v[188:191], v[94:97]
	v_mfma_f32_16x16x32_bf16 v[90:93], v[172:175], v[188:191], v[90:93]
	v_mfma_f32_16x16x32_bf16 v[78:81], v[164:167], v[196:199], v[78:81]
	v_mfma_f32_16x16x32_bf16 v[74:77], v[172:175], v[196:199], v[74:77]
	v_mfma_f32_16x16x32_bf16 v[70:73], v[164:167], v[204:207], v[70:73]
	v_mfma_f32_16x16x32_bf16 v[66:69], v[172:175], v[204:207], v[66:69]
	s_barrier
	s_add_i32 s22, s22, s56
	v_lshl_add_u64 v[208:209], s[48:49], 0, v[0:1]
	s_mov_b32 m0, s22
	ds_read_b128 v[176:179], v143 offset:16384
	ds_read_b128 v[180:183], v143 offset:17408
	ds_read_b128 v[184:187], v143 offset:18432
	ds_read_b128 v[188:191], v143 offset:19456
	ds_read_b128 v[192:195], v143 offset:20480
	ds_read_b128 v[196:199], v143 offset:21504
	ds_read_b128 v[200:203], v143 offset:22528
	ds_read_b128 v[204:207], v143 offset:23552
	global_load_lds_dwordx4 v[208:209], off
	s_add_i32 m0, s22, 0x2000
	s_add_u32 s22, s48, 0x160000
	v_lshl_add_u64 v[210:211], s[48:49], 0, v[130:131]
	s_addc_u32 s23, s49, 0
	s_add_i32 s46, s85, s56
	global_load_lds_dwordx4 v[210:211], off
	v_lshl_add_u64 v[216:217], s[22:23], 0, v[0:1]
	s_mov_b32 m0, s46
	v_lshl_add_u64 v[220:221], s[50:51], 0, v[132:133]
	global_load_lds_dwordx4 v[216:217], off
	v_lshl_add_u64 v[216:217], s[22:23], 0, v[130:131]
	s_add_i32 m0, s46, 0x2000
	s_nop 0
	global_load_lds_dwordx4 v[216:217], off
	v_lshl_add_u64 v[216:217], s[50:51], 0, v[134:135]
	s_mov_b32 m0, s57
	s_nop 0
	global_load_lds_dwordx4 v[216:217], off
	s_mov_b32 m0, s58
	s_nop 0
	global_load_lds_dwordx4 v[220:221], off
	s_waitcnt vmcnt(8)
	s_waitcnt lgkmcnt(0)
	s_barrier
; #define PG8_STAGE(bufoff, gbase, voff) do { _Pragma("unroll") for (int _i = 0; _i < 2; ++_i) \
;         __builtin_amdgcn_global_load_lds((const unsigned*)((const char*)(gbase) + (voff)[_i]), (PG8_LAS unsigned*)(lds + (bufoff) + ldsw + _i * 8192), 16, 0, 0); } while (0)
; #define PG8_LDA(dst, b, h) do { _Pragma("unroll") for (int m = 0; m < 4; ++m) _Pragma("unroll") for (int k = 0; k < 2; ++k) dst[m][k] = *(const PG8_LAS bf16x8*)(lds + PG8_SA(b, h) + aoff + m * 2048 + k * 1024); } while (0)
; #define PG8_LDB(dst, b, h) do { _Pragma("unroll") for (int n = 0; n < 2; ++n) _Pragma("unroll") for (int k = 0; k < 2; ++k) dst[n][k] = *(const PG8_LAS bf16x8*)(lds + PG8_SB(b, h) + boff + n * 2048 + k * 1024); } while (0)
; #define PG8_MMA(ai, bj, At, Bt) do { __builtin_amdgcn_s_setprio(1); _Pragma("unroll") for (int m = 0; m < 4; ++m) _Pragma("unroll") for (int n = 0; n < 2; ++n) _Pragma("unroll") for (int k = 0; k < 2; ++k) \
;         acc[ai][bj][m][n] = __builtin_amdgcn_mfma_f32_16x16x32_bf16(Bt[n][k], At[m][k], acc[ai][bj][m][n], 0, 0, 0); __builtin_amdgcn_s_setprio(0); } while (0)
; #define PG8_WAIT_V(n) asm volatile("s_waitcnt vmcnt(" #n ")" ::: "memory")
; #define PG8_WAIT_L(n) asm volatile("s_waitcnt lgkmcnt(" #n ")" ::: "memory")
; #define PG8_BAR __builtin_amdgcn_s_barrier()
; #define PG8_SCHED __builtin_amdgcn_sched_barrier(0)
; template <class Epi, class Sched, bool ALIGN_EPI = false, bool SP2 = false>
; __device__ __forceinline__ void gemm_phase(PG8_LAS unsigned char* lds, const Gemm g, const Sched& S, const Epi& E) {
;     ...
;             PG8_WAIT_V(8); PG8_WAIT_L(0); PG8_BAR; PG8_MMA(1, 0, At, B0); PG8_MMA(1, 1, At, B1); PG8_BAR; PG8_SCHED;
;             PG8_LDB(B0, 1, 0); PG8_LDB(B1, 1, 1); PG8_SCHED; PG8_LDA(At, 1, 0); PG8_STAGE(PG8_SA(0, 1), a2 + hstep, voffA);
;             PG8_WAIT_V(8); PG8_WAIT_L(0); PG8_BAR; PG8_MMA(0, 0, At, B0); PG8_MMA(0, 1, At, B1); PG8_BAR; PG8_SCHED;
;             PG8_LDA(At, 1, 1); PG8_STAGE(PG8_SB(1, 0), b3, voffB); PG8_STAGE(PG8_SB(1, 1), b3 + hstep, voffB); PG8_STAGE(PG8_SA(1, 0), a3, voffA);
	s_waitcnt lgkmcnt(0)
	v_mfma_f32_16x16x32_bf16 v[62:65], v[144:147], v[176:179], v[62:65]
	v_mfma_f32_16x16x32_bf16 v[58:61], v[152:155], v[176:179], v[58:61]
	v_mfma_f32_16x16x32_bf16 v[54:57], v[144:147], v[184:187], v[54:57]
	v_mfma_f32_16x16x32_bf16 v[50:53], v[152:155], v[184:187], v[50:53]
	v_mfma_f32_16x16x32_bf16 v[38:41], v[144:147], v[192:195], v[38:41]
	v_mfma_f32_16x16x32_bf16 v[34:37], v[152:155], v[192:195], v[34:37]
	v_mfma_f32_16x16x32_bf16 v[22:25], v[144:147], v[200:203], v[22:25]
	v_mfma_f32_16x16x32_bf16 v[18:21], v[152:155], v[200:203], v[18:21]
	v_mfma_f32_16x16x32_bf16 v[62:65], v[148:151], v[180:183], v[62:65]
	v_mfma_f32_16x16x32_bf16 v[58:61], v[156:159], v[180:183], v[58:61]
	v_mfma_f32_16x16x32_bf16 v[54:57], v[148:151], v[188:191], v[54:57]
	v_mfma_f32_16x16x32_bf16 v[50:53], v[156:159], v[188:191], v[50:53]
	v_mfma_f32_16x16x32_bf16 v[38:41], v[148:151], v[196:199], v[38:41]
	v_mfma_f32_16x16x32_bf16 v[34:37], v[156:159], v[196:199], v[34:37]
	v_mfma_f32_16x16x32_bf16 v[22:25], v[148:151], v[204:207], v[22:25]
	v_mfma_f32_16x16x32_bf16 v[18:21], v[156:159], v[204:207], v[18:21]
	v_mfma_f32_16x16x32_bf16 v[46:49], v[160:163], v[176:179], v[46:49]
	v_mfma_f32_16x16x32_bf16 v[42:45], v[168:171], v[176:179], v[42:45]
	v_mfma_f32_16x16x32_bf16 v[30:33], v[160:163], v[184:187], v[30:33]
	v_mfma_f32_16x16x32_bf16 v[26:29], v[168:171], v[184:187], v[26:29]
	v_mfma_f32_16x16x32_bf16 v[14:17], v[160:163], v[192:195], v[14:17]
	v_mfma_f32_16x16x32_bf16 v[10:13], v[168:171], v[192:195], v[10:13]
	v_mfma_f32_16x16x32_bf16 v[6:9], v[160:163], v[200:203], v[6:9]
	v_mfma_f32_16x16x32_bf16 v[2:5], v[168:171], v[200:203], v[2:5]
	v_mfma_f32_16x16x32_bf16 v[46:49], v[164:167], v[180:183], v[46:49]
	v_mfma_f32_16x16x32_bf16 v[42:45], v[172:175], v[180:183], v[42:45]
	v_mfma_f32_16x16x32_bf16 v[30:33], v[164:167], v[188:191], v[30:33]
	v_mfma_f32_16x16x32_bf16 v[26:29], v[172:175], v[188:191], v[26:29]
	v_mfma_f32_16x16x32_bf16 v[14:17], v[164:167], v[196:199], v[14:17]
	v_mfma_f32_16x16x32_bf16 v[10:13], v[172:175], v[196:199], v[10:13]
	v_mfma_f32_16x16x32_bf16 v[6:9], v[164:167], v[204:207], v[6:9]
	v_mfma_f32_16x16x32_bf16 v[2:5], v[172:175], v[204:207], v[2:5]
	s_barrier
	s_add_i32 s46, 0, 0x18000
	s_add_i32 s47, 0, 0x1c000
	v_add_u32_e32 v156, s46, v141
	v_add_u32_e32 v172, s47, v141
	ds_read_b128 v[144:147], v156
	ds_read_b128 v[148:151], v156 offset:1024
	ds_read_b128 v[152:155], v156 offset:2048
	ds_read_b128 v[156:159], v156 offset:3072
	ds_read_b128 v[160:163], v172
	ds_read_b128 v[164:167], v172 offset:1024
	ds_read_b128 v[168:171], v172 offset:2048
	ds_read_b128 v[172:175], v172 offset:3072
	s_add_u32 s22, s50, 0x160000
	s_addc_u32 s23, s51, 0
	s_mov_b32 m0, s59
	v_lshl_add_u64 v[222:223], s[22:23], 0, v[134:135]
	ds_read_b128 v[176:179], v143 offset:32768
	ds_read_b128 v[180:183], v143 offset:33792
	ds_read_b128 v[184:187], v143 offset:34816
	ds_read_b128 v[188:191], v143 offset:35840
	ds_read_b128 v[192:195], v143 offset:36864
	ds_read_b128 v[196:199], v143 offset:37888
	ds_read_b128 v[200:203], v143 offset:38912
	ds_read_b128 v[204:207], v143 offset:39936
	global_load_lds_dwordx4 v[222:223], off
	v_lshl_add_u64 v[222:223], s[22:23], 0, v[132:133]
	s_mov_b32 m0, s74
	s_nop 0
	global_load_lds_dwordx4 v[222:223], off
	s_waitcnt vmcnt(8)
	s_waitcnt lgkmcnt(0)
	s_barrier
	s_waitcnt lgkmcnt(0)
	v_mfma_f32_16x16x32_bf16 v[126:129], v[144:147], v[176:179], v[126:129]
	v_mfma_f32_16x16x32_bf16 v[122:125], v[152:155], v[176:179], v[122:125]
	v_mfma_f32_16x16x32_bf16 v[118:121], v[144:147], v[184:187], v[118:121]
	v_mfma_f32_16x16x32_bf16 v[114:117], v[152:155], v[184:187], v[114:117]
	v_mfma_f32_16x16x32_bf16 v[102:105], v[144:147], v[192:195], v[102:105]
	v_mfma_f32_16x16x32_bf16 v[98:101], v[152:155], v[192:195], v[98:101]
	v_mfma_f32_16x16x32_bf16 v[86:89], v[144:147], v[200:203], v[86:89]
	v_mfma_f32_16x16x32_bf16 v[82:85], v[152:155], v[200:203], v[82:85]
	v_mfma_f32_16x16x32_bf16 v[126:129], v[148:151], v[180:183], v[126:129]
	v_mfma_f32_16x16x32_bf16 v[122:125], v[156:159], v[180:183], v[122:125]
	v_mfma_f32_16x16x32_bf16 v[118:121], v[148:151], v[188:191], v[118:121]
	v_mfma_f32_16x16x32_bf16 v[114:117], v[156:159], v[188:191], v[114:117]
	v_mfma_f32_16x16x32_bf16 v[102:105], v[148:151], v[196:199], v[102:105]
	v_mfma_f32_16x16x32_bf16 v[98:101], v[156:159], v[196:199], v[98:101]
	v_mfma_f32_16x16x32_bf16 v[86:89], v[148:151], v[204:207], v[86:89]
	v_mfma_f32_16x16x32_bf16 v[82:85], v[156:159], v[204:207], v[82:85]
	v_mfma_f32_16x16x32_bf16 v[110:113], v[160:163], v[176:179], v[110:113]
	v_mfma_f32_16x16x32_bf16 v[106:109], v[168:171], v[176:179], v[106:109]
	v_mfma_f32_16x16x32_bf16 v[94:97], v[160:163], v[184:187], v[94:97]
	v_mfma_f32_16x16x32_bf16 v[90:93], v[168:171], v[184:187], v[90:93]
	v_mfma_f32_16x16x32_bf16 v[78:81], v[160:163], v[192:195], v[78:81]
	v_mfma_f32_16x16x32_bf16 v[74:77], v[168:171], v[192:195], v[74:77]
	v_mfma_f32_16x16x32_bf16 v[70:73], v[160:163], v[200:203], v[70:73]
	v_mfma_f32_16x16x32_bf16 v[66:69], v[168:171], v[200:203], v[66:69]
	v_mfma_f32_16x16x32_bf16 v[110:113], v[164:167], v[180:183], v[110:113]
	v_mfma_f32_16x16x32_bf16 v[106:109], v[172:175], v[180:183], v[106:109]
	v_mfma_f32_16x16x32_bf16 v[94:97], v[164:167], v[188:191], v[94:97]
	v_mfma_f32_16x16x32_bf16 v[90:93], v[172:175], v[188:191], v[90:93]
	v_mfma_f32_16x16x32_bf16 v[78:81], v[164:167], v[196:199], v[78:81]
	v_mfma_f32_16x16x32_bf16 v[74:77], v[172:175], v[196:199], v[74:77]
	v_mfma_f32_16x16x32_bf16 v[70:73], v[164:167], v[204:207], v[70:73]
	v_mfma_f32_16x16x32_bf16 v[66:69], v[172:175], v[204:207], v[66:69]
	s_barrier
; #define PG8_STAGE(bufoff, gbase, voff) do { _Pragma("unroll") for (int _i = 0; _i < 2; ++_i) \
;         __builtin_amdgcn_global_load_lds((const unsigned*)((const char*)(gbase) + (voff)[_i]), (PG8_LAS unsigned*)(lds + (bufoff) + ldsw + _i * 8192), 16, 0, 0); } while (0)
; #define PG8_LDA(dst, b, h) do { _Pragma("unroll") for (int m = 0; m < 4; ++m) _Pragma("unroll") for (int k = 0; k < 2; ++k) dst[m][k] = *(const PG8_LAS bf16x8*)(lds + PG8_SA(b, h) + aoff + m * 2048 + k * 1024); } while (0)
; #define PG8_MMA(ai, bj, At, Bt) do { __builtin_amdgcn_s_setprio(1); _Pragma("unroll") for (int m = 0; m < 4; ++m) _Pragma("unroll") for (int n = 0; n < 2; ++n) _Pragma("unroll") for (int k = 0; k < 2; ++k) \
;         acc[ai][bj][m][n] = __builtin_amdgcn_mfma_f32_16x16x32_bf16(Bt[n][k], At[m][k], acc[ai][bj][m][n], 0, 0, 0); __builtin_amdgcn_s_setprio(0); } while (0)
; #define PG8_WAIT_V(n) asm volatile("s_waitcnt vmcnt(" #n ")" ::: "memory")
; #define PG8_WAIT_L(n) asm volatile("s_waitcnt lgkmcnt(" #n ")" ::: "memory")
; #define PG8_BAR __builtin_amdgcn_s_barrier()
; #define PG8_SCHED __builtin_amdgcn_sched_barrier(0)
; template <class Epi, class Sched, bool ALIGN_EPI = false, bool SP2 = false>
; __device__ __forceinline__ void gemm_phase(PG8_LAS unsigned char* lds, const Gemm g, const Sched& S, const Epi& E) {
;     ...
;             PG8_LDA(At, 1, 1); PG8_STAGE(PG8_SB(1, 0), b3, voffB); PG8_STAGE(PG8_SB(1, 1), b3 + hstep, voffB); PG8_STAGE(PG8_SA(1, 0), a3, voffA);
;             PG8_WAIT_V(8); PG8_WAIT_L(0); PG8_BAR; PG8_MMA(1, 0, At, B0); PG8_MMA(1, 1, At, B1); PG8_BAR; PG8_SCHED;
	s_add_i32 s22, s46, s56
	v_lshl_add_u64 v[208:209], v[208:209], 0, s[30:31]
	s_mov_b32 m0, s22
	ds_read_b128 v[176:179], v143 offset:49152
	ds_read_b128 v[180:183], v143 offset:50176
	ds_read_b128 v[184:187], v143 offset:51200
	ds_read_b128 v[188:191], v143 offset:52224
	ds_read_b128 v[192:195], v143 offset:53248
	ds_read_b128 v[196:199], v143 offset:54272
	ds_read_b128 v[200:203], v143 offset:55296
	ds_read_b128 v[204:207], v143 offset:56320
	global_load_lds_dwordx4 v[208:209], off
	s_add_i32 m0, s22, 0x2000
	s_add_u32 s22, s48, 0x160080
	v_lshl_add_u64 v[208:209], v[210:211], 0, s[30:31]
	s_addc_u32 s23, s49, 0
	s_add_i32 s46, s47, s56
	global_load_lds_dwordx4 v[208:209], off
	v_lshl_add_u64 v[208:209], s[22:23], 0, v[0:1]
	s_mov_b32 m0, s46
	s_nop 0
	global_load_lds_dwordx4 v[208:209], off
	v_lshl_add_u64 v[208:209], s[22:23], 0, v[130:131]
	s_add_i32 m0, s46, 0x2000
	s_nop 0
	global_load_lds_dwordx4 v[208:209], off
	v_lshl_add_u64 v[208:209], v[216:217], 0, s[30:31]
	s_mov_b32 m0, s75
	s_nop 0
	global_load_lds_dwordx4 v[208:209], off
	v_lshl_add_u64 v[208:209], v[220:221], 0, s[30:31]
	s_mov_b32 m0, s76
	s_nop 0
	global_load_lds_dwordx4 v[208:209], off
	s_waitcnt vmcnt(8)
	s_waitcnt lgkmcnt(0)
	s_barrier
	s_waitcnt lgkmcnt(0)
	v_mfma_f32_16x16x32_bf16 v[62:65], v[144:147], v[176:179], v[62:65]
	v_mfma_f32_16x16x32_bf16 v[58:61], v[152:155], v[176:179], v[58:61]
	v_mfma_f32_16x16x32_bf16 v[54:57], v[144:147], v[184:187], v[54:57]
	v_mfma_f32_16x16x32_bf16 v[50:53], v[152:155], v[184:187], v[50:53]
	v_mfma_f32_16x16x32_bf16 v[38:41], v[144:147], v[192:195], v[38:41]
	v_mfma_f32_16x16x32_bf16 v[34:37], v[152:155], v[192:195], v[34:37]
	v_mfma_f32_16x16x32_bf16 v[22:25], v[144:147], v[200:203], v[22:25]
	v_mfma_f32_16x16x32_bf16 v[18:21], v[152:155], v[200:203], v[18:21]
	v_mfma_f32_16x16x32_bf16 v[62:65], v[148:151], v[180:183], v[62:65]
	v_mfma_f32_16x16x32_bf16 v[58:61], v[156:159], v[180:183], v[58:61]
	v_mfma_f32_16x16x32_bf16 v[54:57], v[148:151], v[188:191], v[54:57]
	v_mfma_f32_16x16x32_bf16 v[50:53], v[156:159], v[188:191], v[50:53]
	v_mfma_f32_16x16x32_bf16 v[38:41], v[148:151], v[196:199], v[38:41]
	v_mfma_f32_16x16x32_bf16 v[34:37], v[156:159], v[196:199], v[34:37]
	v_mfma_f32_16x16x32_bf16 v[22:25], v[148:151], v[204:207], v[22:25]
	v_mfma_f32_16x16x32_bf16 v[18:21], v[156:159], v[204:207], v[18:21]
	v_mfma_f32_16x16x32_bf16 v[46:49], v[160:163], v[176:179], v[46:49]
	v_mfma_f32_16x16x32_bf16 v[42:45], v[168:171], v[176:179], v[42:45]
	v_mfma_f32_16x16x32_bf16 v[30:33], v[160:163], v[184:187], v[30:33]
	v_mfma_f32_16x16x32_bf16 v[26:29], v[168:171], v[184:187], v[26:29]
	v_mfma_f32_16x16x32_bf16 v[14:17], v[160:163], v[192:195], v[14:17]
	v_mfma_f32_16x16x32_bf16 v[10:13], v[168:171], v[192:195], v[10:13]
	v_mfma_f32_16x16x32_bf16 v[6:9], v[160:163], v[200:203], v[6:9]
	v_mfma_f32_16x16x32_bf16 v[2:5], v[168:171], v[200:203], v[2:5]
	v_mfma_f32_16x16x32_bf16 v[46:49], v[164:167], v[180:183], v[46:49]
	v_mfma_f32_16x16x32_bf16 v[42:45], v[172:175], v[180:183], v[42:45]
	v_mfma_f32_16x16x32_bf16 v[30:33], v[164:167], v[188:191], v[30:33]
	v_mfma_f32_16x16x32_bf16 v[26:29], v[172:175], v[188:191], v[26:29]
	v_mfma_f32_16x16x32_bf16 v[14:17], v[164:167], v[196:199], v[14:17]
	v_mfma_f32_16x16x32_bf16 v[10:13], v[172:175], v[196:199], v[10:13]
	v_mfma_f32_16x16x32_bf16 v[6:9], v[164:167], v[204:207], v[6:9]
	v_mfma_f32_16x16x32_bf16 v[2:5], v[172:175], v[204:207], v[2:5]
	s_barrier
	s_add_i32 s84, s84, 2
	s_add_u32 s82, s82, 0x100
	s_addc_u32 s83, s83, 0
	s_cmpk_gt_u32 s84, 0x55
	s_mov_b64 s[46:47], s[34:35]
	s_cbranch_scc0 .LBB0_783
	s_and_b64 vcc, exec, s[42:43]
	s_cbranch_vccz .LBB0_786
	s_barrier
